# phase 4 epilogues rewritten by hand: accumulators exchanged between 16-lane rows once, all gate/M accesses are 16-byte loads/stores, next block's loads issued before the current block's math
# speedup vs baseline: 1.0464x; 1.0139x over previous
; #define PG8_STAGE(bufoff, gbase, voff) do { _Pragma("unroll") for (int _i = 0; _i < 2; ++_i) \
;         __builtin_amdgcn_global_load_lds((const unsigned*)((const char*)(gbase) + (voff)[_i]), (PG8_LAS unsigned*)(lds + (bufoff) + ldsw + _i * 8192), 16, 0, 0); } while (0)
; #define PG8_LDA(dst, b, h) do { _Pragma("unroll") for (int m = 0; m < 4; ++m) _Pragma("unroll") for (int k = 0; k < 2; ++k) dst[m][k] = *(const PG8_LAS bf16x8*)(lds + PG8_SA(b, h) + aoff + m * 2048 + k * 1024); } while (0)
; #define PG8_LDB(dst, b, h) do { _Pragma("unroll") for (int n = 0; n < 2; ++n) _Pragma("unroll") for (int k = 0; k < 2; ++k) dst[n][k] = *(const PG8_LAS bf16x8*)(lds + PG8_SB(b, h) + boff + n * 2048 + k * 1024); } while (0)
; #define PG8_MMA(ai, bj, At, Bt) do { __builtin_amdgcn_s_setprio(1); _Pragma("unroll") for (int m = 0; m < 4; ++m) _Pragma("unroll") for (int n = 0; n < 2; ++n) _Pragma("unroll") for (int k = 0; k < 2; ++k) \
;         acc[ai][bj][m][n] = __builtin_amdgcn_mfma_f32_16x16x32_bf16(Bt[n][k], At[m][k], acc[ai][bj][m][n], 0, 0, 0); __builtin_amdgcn_s_setprio(0); } while (0)
; #define PG8_WAIT_V(n) asm volatile("s_waitcnt vmcnt(" #n ")" ::: "memory")
; #define PG8_WAIT_L(n) asm volatile("s_waitcnt lgkmcnt(" #n ")" ::: "memory")
; #define PG8_BAR __builtin_amdgcn_s_barrier()
; #define PG8_SCHED __builtin_amdgcn_sched_barrier(0)
; template <class Epi, class Sched>
; __device__ __forceinline__ void gemm_phase(PG8_LAS unsigned char* lds, const Gemm g, const Sched& S, const Epi& E) {
;     ...
;             PG8_LDB(B0, 0, 0); PG8_SCHED; PG8_LDA(At, 0, 0); PG8_STAGE(PG8_SA(1, 1), a1 + hstep, voffA);
;             PG8_WAIT_L(8); PG8_BAR; PG8_WAIT_L(0); PG8_MMA(0, 0, At, B0); PG8_BAR; PG8_SCHED;
;             PG8_LDB(B1, 0, 1); PG8_STAGE(PG8_SB(0, 0), b2, voffB);
;             PG8_BAR; PG8_WAIT_L(0); PG8_MMA(0, 1, At, B1); PG8_BAR;
;             PG8_LDA(At, 0, 1); PG8_STAGE(PG8_SA(0, 0), a2, voffA);
;             PG8_BAR; PG8_WAIT_L(0); PG8_MMA(1, 0, At, B0); PG8_BAR; PG8_SCHED;
;             PG8_STAGE(PG8_SB(0, 1), b2 + hstep, voffB);
;             PG8_WAIT_V(6); PG8_BAR; PG8_MMA(1, 1, At, B1); PG8_BAR;
.LBB0_694:
	ds_read_b128 v[138:141], v157
	ds_read_b128 v[142:145], v158
	ds_read_b128 v[174:177], v159
	ds_read_b128 v[178:181], v160
	s_add_u32 s30, s28, 0xfffe0080
	s_addc_u32 s31, s29, -1
	s_cmp_eq_u32 s63, 4
	s_cselect_b32 s35, s17, s31
	s_cselect_b32 s34, s59, s30
	s_cselect_b32 s31, s15, s62
	s_cselect_b32 s30, s60, s61
	s_mov_b32 m0, s57
	v_lshl_add_u64 v[214:215], s[28:29], 0, v[134:135]
	ds_read_b128 v[182:185], v155
	ds_read_b128 v[186:189], v155 offset:1024
	ds_read_b128 v[190:193], v155 offset:2048
	ds_read_b128 v[194:197], v155 offset:3072
	ds_read_b128 v[198:201], v155 offset:4096
	ds_read_b128 v[202:205], v155 offset:5120
	ds_read_b128 v[206:209], v155 offset:6144
	ds_read_b128 v[210:213], v155 offset:7168
	global_load_lds_dwordx4 v[214:215], off
	v_lshl_add_u64 v[214:215], s[28:29], 0, v[136:137]
	s_mov_b32 m0, s58
	s_nop 0
	global_load_lds_dwordx4 v[214:215], off
	s_waitcnt lgkmcnt(8)
	s_barrier
	s_waitcnt lgkmcnt(0)
	s_setprio 1
	s_waitcnt lgkmcnt(0)
	v_mfma_f32_16x16x32_bf16 v[126:129], v[138:141], v[182:185], v[126:129]
	v_mfma_f32_16x16x32_bf16 v[122:125], v[174:177], v[182:185], v[122:125]
	v_mfma_f32_16x16x32_bf16 v[118:121], v[138:141], v[190:193], v[118:121]
	v_mfma_f32_16x16x32_bf16 v[106:109], v[174:177], v[190:193], v[106:109]
	v_mfma_f32_16x16x32_bf16 v[98:101], v[138:141], v[198:201], v[98:101]
	v_mfma_f32_16x16x32_bf16 v[94:97], v[174:177], v[198:201], v[94:97]
	v_mfma_f32_16x16x32_bf16 v[86:89], v[138:141], v[206:209], v[86:89]
	v_mfma_f32_16x16x32_bf16 v[78:81], v[174:177], v[206:209], v[78:81]
	v_mfma_f32_16x16x32_bf16 v[126:129], v[142:145], v[186:189], v[126:129]
	v_mfma_f32_16x16x32_bf16 v[122:125], v[178:181], v[186:189], v[122:125]
	v_mfma_f32_16x16x32_bf16 v[118:121], v[142:145], v[194:197], v[118:121]
	v_mfma_f32_16x16x32_bf16 v[106:109], v[178:181], v[194:197], v[106:109]
	v_mfma_f32_16x16x32_bf16 v[98:101], v[142:145], v[202:205], v[98:101]
	v_mfma_f32_16x16x32_bf16 v[94:97], v[178:181], v[202:205], v[94:97]
	v_mfma_f32_16x16x32_bf16 v[86:89], v[142:145], v[210:213], v[86:89]
	v_mfma_f32_16x16x32_bf16 v[78:81], v[178:181], v[210:213], v[78:81]
	s_setprio 0
	s_barrier
	s_mov_b32 m0, s25
	v_lshl_add_u64 v[230:231], s[30:31], 0, v[130:131]
	ds_read_b128 v[214:217], v161
	ds_read_b128 v[218:221], v162
	ds_read_b128 v[222:225], v163
	ds_read_b128 v[226:229], v164
	global_load_lds_dwordx4 v[230:231], off
	v_lshl_add_u64 v[232:233], s[30:31], 0, v[132:133]
	s_mov_b32 m0, s27
	s_nop 0
	global_load_lds_dwordx4 v[232:233], off
	s_barrier
	s_waitcnt lgkmcnt(0)
	s_setprio 1
	s_waitcnt lgkmcnt(0)
	v_mfma_f32_16x16x32_bf16 v[114:117], v[214:217], v[182:185], v[114:117]
	v_mfma_f32_16x16x32_bf16 v[110:113], v[222:225], v[182:185], v[110:113]
	v_mfma_f32_16x16x32_bf16 v[102:105], v[214:217], v[190:193], v[102:105]
	v_mfma_f32_16x16x32_bf16 v[90:93], v[222:225], v[190:193], v[90:93]
	v_mfma_f32_16x16x32_bf16 v[82:85], v[214:217], v[198:201], v[82:85]
	v_mfma_f32_16x16x32_bf16 v[70:73], v[222:225], v[198:201], v[70:73]
	v_mfma_f32_16x16x32_bf16 v[74:77], v[214:217], v[206:209], v[74:77]
	v_mfma_f32_16x16x32_bf16 v[66:69], v[222:225], v[206:209], v[66:69]
	v_mfma_f32_16x16x32_bf16 v[114:117], v[218:221], v[186:189], v[114:117]
	v_mfma_f32_16x16x32_bf16 v[110:113], v[226:229], v[186:189], v[110:113]
	v_mfma_f32_16x16x32_bf16 v[102:105], v[218:221], v[194:197], v[102:105]
	v_mfma_f32_16x16x32_bf16 v[90:93], v[226:229], v[194:197], v[90:93]
	v_mfma_f32_16x16x32_bf16 v[82:85], v[218:221], v[202:205], v[82:85]
	v_mfma_f32_16x16x32_bf16 v[70:73], v[226:229], v[202:205], v[70:73]
	v_mfma_f32_16x16x32_bf16 v[74:77], v[218:221], v[210:213], v[74:77]
	v_mfma_f32_16x16x32_bf16 v[66:69], v[226:229], v[210:213], v[66:69]
	s_setprio 0
	s_mov_b32 m0, s40
	v_lshl_add_u64 v[234:235], s[34:35], 0, v[130:131]
	s_barrier
	ds_read_b128 v[182:185], v155 offset:16384
	ds_read_b128 v[186:189], v155 offset:17408
	ds_read_b128 v[190:193], v155 offset:18432
	ds_read_b128 v[194:197], v155 offset:19456
	ds_read_b128 v[198:201], v155 offset:20480
	ds_read_b128 v[202:205], v155 offset:21504
	ds_read_b128 v[206:209], v155 offset:22528
	ds_read_b128 v[210:213], v155 offset:23552
	global_load_lds_dwordx4 v[234:235], off
	v_lshl_add_u64 v[236:237], s[34:35], 0, v[132:133]
	s_mov_b32 m0, s41
	s_nop 0
	global_load_lds_dwordx4 v[236:237], off
	s_barrier
	s_waitcnt lgkmcnt(0)
	s_setprio 1
	s_waitcnt lgkmcnt(0)
	v_mfma_f32_16x16x32_bf16 v[62:65], v[138:141], v[182:185], v[62:65]
	v_mfma_f32_16x16x32_bf16 v[58:61], v[174:177], v[182:185], v[58:61]
	v_mfma_f32_16x16x32_bf16 v[50:53], v[138:141], v[190:193], v[50:53]
	v_mfma_f32_16x16x32_bf16 v[42:45], v[174:177], v[190:193], v[42:45]
	v_mfma_f32_16x16x32_bf16 v[30:33], v[138:141], v[198:201], v[30:33]
	v_mfma_f32_16x16x32_bf16 v[26:29], v[174:177], v[198:201], v[26:29]
	v_mfma_f32_16x16x32_bf16 v[14:17], v[138:141], v[206:209], v[14:17]
	v_mfma_f32_16x16x32_bf16 v[10:13], v[174:177], v[206:209], v[10:13]
	v_mfma_f32_16x16x32_bf16 v[62:65], v[142:145], v[186:189], v[62:65]
	v_mfma_f32_16x16x32_bf16 v[58:61], v[178:181], v[186:189], v[58:61]
	v_mfma_f32_16x16x32_bf16 v[50:53], v[142:145], v[194:197], v[50:53]
	v_mfma_f32_16x16x32_bf16 v[42:45], v[178:181], v[194:197], v[42:45]
	v_mfma_f32_16x16x32_bf16 v[30:33], v[142:145], v[202:205], v[30:33]
	v_mfma_f32_16x16x32_bf16 v[26:29], v[178:181], v[202:205], v[26:29]
	v_mfma_f32_16x16x32_bf16 v[14:17], v[142:145], v[210:213], v[14:17]
	v_mfma_f32_16x16x32_bf16 v[10:13], v[178:181], v[210:213], v[10:13]
	s_setprio 0
	s_barrier
; #define PG8_STAGE(bufoff, gbase, voff) do { _Pragma("unroll") for (int _i = 0; _i < 2; ++_i) \
;         __builtin_amdgcn_global_load_lds((const unsigned*)((const char*)(gbase) + (voff)[_i]), (PG8_LAS unsigned*)(lds + (bufoff) + ldsw + _i * 8192), 16, 0, 0); } while (0)
; #define PG8_LDA(dst, b, h) do { _Pragma("unroll") for (int m = 0; m < 4; ++m) _Pragma("unroll") for (int k = 0; k < 2; ++k) dst[m][k] = *(const PG8_LAS bf16x8*)(lds + PG8_SA(b, h) + aoff + m * 2048 + k * 1024); } while (0)
; #define PG8_LDB(dst, b, h) do { _Pragma("unroll") for (int n = 0; n < 2; ++n) _Pragma("unroll") for (int k = 0; k < 2; ++k) dst[n][k] = *(const PG8_LAS bf16x8*)(lds + PG8_SB(b, h) + boff + n * 2048 + k * 1024); } while (0)
; #define PG8_MMA(ai, bj, At, Bt) do { __builtin_amdgcn_s_setprio(1); _Pragma("unroll") for (int m = 0; m < 4; ++m) _Pragma("unroll") for (int n = 0; n < 2; ++n) _Pragma("unroll") for (int k = 0; k < 2; ++k) \
;         acc[ai][bj][m][n] = __builtin_amdgcn_mfma_f32_16x16x32_bf16(Bt[n][k], At[m][k], acc[ai][bj][m][n], 0, 0, 0); __builtin_amdgcn_s_setprio(0); } while (0)
; #define PG8_WAIT_L(n) asm volatile("s_waitcnt lgkmcnt(" #n ")" ::: "memory")
; #define PG8_BAR __builtin_amdgcn_s_barrier()
; #define PG8_SCHED __builtin_amdgcn_sched_barrier(0)
; template <class Epi, class Sched>
; __device__ __forceinline__ void gemm_phase(PG8_LAS unsigned char* lds, const Gemm g, const Sched& S, const Epi& E) {
;     ...
;             PG8_LDB(B0, 1, 0); PG8_SCHED; PG8_LDA(At, 1, 0); PG8_STAGE(PG8_SA(0, 1), a2 + hstep, voffA);
;             PG8_WAIT_L(8); PG8_BAR; PG8_WAIT_L(0); PG8_MMA(0, 0, At, B0); PG8_BAR; PG8_SCHED;
;             PG8_LDB(B1, 1, 1); PG8_STAGE(PG8_SB(1, 0), b3, voffB);
;             PG8_BAR; PG8_WAIT_L(0); PG8_MMA(0, 1, At, B1); PG8_BAR;
;             PG8_LDA(At, 1, 1); PG8_STAGE(PG8_SA(1, 0), a3, voffA);
;             PG8_BAR; PG8_WAIT_L(0); PG8_MMA(1, 0, At, B0); PG8_BAR; PG8_SCHED;
	s_add_u32 s64, s30, 0x20000
	s_addc_u32 s65, s31, 0
	s_mov_b32 m0, s42
	v_lshl_add_u64 v[138:139], s[64:65], 0, v[130:131]
	global_load_lds_dwordx4 v[138:139], off
	v_lshl_add_u64 v[138:139], s[64:65], 0, v[132:133]
	s_mov_b32 m0, s43
	s_nop 0
	global_load_lds_dwordx4 v[138:139], off
	s_waitcnt vmcnt(6)
	s_barrier
	s_setprio 1
	v_mfma_f32_16x16x32_bf16 v[54:57], v[214:217], v[182:185], v[54:57]
	v_mfma_f32_16x16x32_bf16 v[46:49], v[222:225], v[182:185], v[46:49]
	v_mfma_f32_16x16x32_bf16 v[38:41], v[214:217], v[190:193], v[38:41]
	v_mfma_f32_16x16x32_bf16 v[34:37], v[222:225], v[190:193], v[34:37]
	v_mfma_f32_16x16x32_bf16 v[22:25], v[214:217], v[198:201], v[22:25]
	v_mfma_f32_16x16x32_bf16 v[18:21], v[222:225], v[198:201], v[18:21]
	v_mfma_f32_16x16x32_bf16 v[6:9], v[214:217], v[206:209], v[6:9]
	v_mfma_f32_16x16x32_bf16 v[2:5], v[222:225], v[206:209], v[2:5]
	v_mfma_f32_16x16x32_bf16 v[54:57], v[218:221], v[186:189], v[54:57]
	v_mfma_f32_16x16x32_bf16 v[46:49], v[226:229], v[186:189], v[46:49]
	v_mfma_f32_16x16x32_bf16 v[38:41], v[218:221], v[194:197], v[38:41]
	v_mfma_f32_16x16x32_bf16 v[34:37], v[226:229], v[194:197], v[34:37]
	v_mfma_f32_16x16x32_bf16 v[22:25], v[218:221], v[202:205], v[22:25]
	v_mfma_f32_16x16x32_bf16 v[18:21], v[226:229], v[202:205], v[18:21]
	v_mfma_f32_16x16x32_bf16 v[6:9], v[218:221], v[210:213], v[6:9]
	v_mfma_f32_16x16x32_bf16 v[2:5], v[226:229], v[210:213], v[2:5]
	s_setprio 0
	s_barrier
	ds_read_b128 v[138:141], v165
	ds_read_b128 v[142:145], v166
	ds_read_b128 v[174:177], v167
	ds_read_b128 v[178:181], v168
	s_add_u32 s34, s34, 0x20000
	s_addc_u32 s35, s35, 0
	s_mov_b32 m0, s44
	v_lshl_add_u64 v[214:215], s[34:35], 0, v[130:131]
	ds_read_b128 v[182:185], v155 offset:32768
	ds_read_b128 v[186:189], v155 offset:33792
	ds_read_b128 v[190:193], v155 offset:34816
	ds_read_b128 v[194:197], v155 offset:35840
	ds_read_b128 v[198:201], v155 offset:36864
	ds_read_b128 v[202:205], v155 offset:37888
	ds_read_b128 v[206:209], v155 offset:38912
	ds_read_b128 v[210:213], v155 offset:39936
	global_load_lds_dwordx4 v[214:215], off
	v_lshl_add_u64 v[214:215], s[34:35], 0, v[132:133]
	s_mov_b32 m0, s45
	s_nop 0
	global_load_lds_dwordx4 v[214:215], off
	s_waitcnt lgkmcnt(8)
	s_barrier
	s_waitcnt lgkmcnt(0)
	s_setprio 1
	s_waitcnt lgkmcnt(0)
	v_mfma_f32_16x16x32_bf16 v[126:129], v[138:141], v[182:185], v[126:129]
	v_mfma_f32_16x16x32_bf16 v[122:125], v[174:177], v[182:185], v[122:125]
	v_mfma_f32_16x16x32_bf16 v[118:121], v[138:141], v[190:193], v[118:121]
	v_mfma_f32_16x16x32_bf16 v[106:109], v[174:177], v[190:193], v[106:109]
	v_mfma_f32_16x16x32_bf16 v[98:101], v[138:141], v[198:201], v[98:101]
	v_mfma_f32_16x16x32_bf16 v[94:97], v[174:177], v[198:201], v[94:97]
	v_mfma_f32_16x16x32_bf16 v[86:89], v[138:141], v[206:209], v[86:89]
	v_mfma_f32_16x16x32_bf16 v[78:81], v[174:177], v[206:209], v[78:81]
	v_mfma_f32_16x16x32_bf16 v[126:129], v[142:145], v[186:189], v[126:129]
	v_mfma_f32_16x16x32_bf16 v[122:125], v[178:181], v[186:189], v[122:125]
	v_mfma_f32_16x16x32_bf16 v[118:121], v[142:145], v[194:197], v[118:121]
	v_mfma_f32_16x16x32_bf16 v[106:109], v[178:181], v[194:197], v[106:109]
	v_mfma_f32_16x16x32_bf16 v[98:101], v[142:145], v[202:205], v[98:101]
	v_mfma_f32_16x16x32_bf16 v[94:97], v[178:181], v[202:205], v[94:97]
	v_mfma_f32_16x16x32_bf16 v[86:89], v[142:145], v[210:213], v[86:89]
	v_mfma_f32_16x16x32_bf16 v[78:81], v[178:181], v[210:213], v[78:81]
	s_setprio 0
	s_barrier
	s_mov_b32 m0, s46
	v_lshl_add_u64 v[230:231], v[230:231], 0, s[8:9]
	ds_read_b128 v[214:217], v169
	ds_read_b128 v[218:221], v170
	ds_read_b128 v[222:225], v171
	ds_read_b128 v[226:229], v172
	global_load_lds_dwordx4 v[230:231], off
	v_lshl_add_u64 v[230:231], v[232:233], 0, s[8:9]
	s_mov_b32 m0, s47
	s_nop 0
	global_load_lds_dwordx4 v[230:231], off
	s_barrier
	s_waitcnt lgkmcnt(0)
	s_setprio 1
	s_waitcnt lgkmcnt(0)
	v_mfma_f32_16x16x32_bf16 v[114:117], v[214:217], v[182:185], v[114:117]
	v_mfma_f32_16x16x32_bf16 v[110:113], v[222:225], v[182:185], v[110:113]
	v_mfma_f32_16x16x32_bf16 v[102:105], v[214:217], v[190:193], v[102:105]
	v_mfma_f32_16x16x32_bf16 v[90:93], v[222:225], v[190:193], v[90:93]
	v_mfma_f32_16x16x32_bf16 v[82:85], v[214:217], v[198:201], v[82:85]
	v_mfma_f32_16x16x32_bf16 v[70:73], v[222:225], v[198:201], v[70:73]
	v_mfma_f32_16x16x32_bf16 v[74:77], v[214:217], v[206:209], v[74:77]
	v_mfma_f32_16x16x32_bf16 v[66:69], v[222:225], v[206:209], v[66:69]
	v_mfma_f32_16x16x32_bf16 v[114:117], v[218:221], v[186:189], v[114:117]
	v_mfma_f32_16x16x32_bf16 v[110:113], v[226:229], v[186:189], v[110:113]
	v_mfma_f32_16x16x32_bf16 v[102:105], v[218:221], v[194:197], v[102:105]
	v_mfma_f32_16x16x32_bf16 v[90:93], v[226:229], v[194:197], v[90:93]
	v_mfma_f32_16x16x32_bf16 v[82:85], v[218:221], v[202:205], v[82:85]
	v_mfma_f32_16x16x32_bf16 v[70:73], v[226:229], v[202:205], v[70:73]
	v_mfma_f32_16x16x32_bf16 v[74:77], v[218:221], v[210:213], v[74:77]
	v_mfma_f32_16x16x32_bf16 v[66:69], v[226:229], v[210:213], v[66:69]
	s_setprio 0
	s_mov_b32 m0, s48
	v_lshl_add_u64 v[230:231], v[234:235], 0, s[8:9]
	s_barrier
	ds_read_b128 v[182:185], v155 offset:49152
	ds_read_b128 v[186:189], v155 offset:50176
	ds_read_b128 v[190:193], v155 offset:51200
	ds_read_b128 v[194:197], v155 offset:52224
	ds_read_b128 v[198:201], v155 offset:53248
	ds_read_b128 v[202:205], v155 offset:54272
	ds_read_b128 v[206:209], v155 offset:55296
	ds_read_b128 v[210:213], v155 offset:56320
	global_load_lds_dwordx4 v[230:231], off
	v_lshl_add_u64 v[230:231], v[236:237], 0, s[8:9]
	s_mov_b32 m0, s49
	s_nop 0
	global_load_lds_dwordx4 v[230:231], off
	s_barrier
; __device__ __forceinline__ float bflo(uint32_t v) { return __uint_as_float(v << 16); }
; __device__ __forceinline__ float bfhi(uint32_t v) { return __uint_as_float(v & 0xFFFF0000u); }
; #define PG8_STAGE(bufoff, gbase, voff) do { _Pragma("unroll") for (int _i = 0; _i < 2; ++_i) \
;         __builtin_amdgcn_global_load_lds((const unsigned*)((const char*)(gbase) + (voff)[_i]), (PG8_LAS unsigned*)(lds + (bufoff) + ldsw + _i * 8192), 16, 0, 0); } while (0)
; #define PG8_MMA(ai, bj, At, Bt) do { __builtin_amdgcn_s_setprio(1); _Pragma("unroll") for (int m = 0; m < 4; ++m) _Pragma("unroll") for (int n = 0; n < 2; ++n) _Pragma("unroll") for (int k = 0; k < 2; ++k) \
;         acc[ai][bj][m][n] = __builtin_amdgcn_mfma_f32_16x16x32_bf16(Bt[n][k], At[m][k], acc[ai][bj][m][n], 0, 0, 0); __builtin_amdgcn_s_setprio(0); } while (0)
; #define PG8_WAIT_V(n) asm volatile("s_waitcnt vmcnt(" #n ")" ::: "memory")
; #define PG8_WAIT_L(n) asm volatile("s_waitcnt lgkmcnt(" #n ")" ::: "memory")
; #define PG8_BAR __builtin_amdgcn_s_barrier()
; #define PG8_SCHED __builtin_amdgcn_sched_barrier(0)
; template <class Epi, class Sched>
; __device__ __forceinline__ void gemm_phase(PG8_LAS unsigned char* lds, const Gemm g, const Sched& S, const Epi& E) {
;     ...
;             PG8_BAR; PG8_WAIT_L(0); PG8_MMA(1, 0, At, B0); PG8_BAR; PG8_SCHED;
;             PG8_STAGE(PG8_SB(1, 1), b3 + hstep, voffB);
;             PG8_WAIT_V(6); PG8_BAR; PG8_MMA(1, 1, At, B1); PG8_BAR;
;   __device__ __forceinline__ void operator()(const acc8_t& acc, const pg8::Unit& u, int wr, int wc, int fr, int fq) const {
;     const u16* GA = (const u16*)(ws + OFF_GA); u16* M = (u16*)(ws + OFF_M);
; #pragma unroll
;     for (int ai = 0; ai < 2; ai++)
; #pragma unroll
;       for (int m = 0; m < 4; m++) {
;         const size_t token = EPI_TOKEN(u, ai, m);
; #pragma unroll
;         for (int bj = 0; bj < 2; bj++)
; #pragma unroll
;           for (int n = 0; n < 2; n++) {
;             const int f = EPI_COL(u, bj, n);
;             const uint2 ga = *(const uint2*)(GA + token * 1024 + f);
;             uint2 o;
;             o.x = pack2(bflo(ga.x) * acc[ai][bj][m][n][0], bfhi(ga.x) * acc[ai][bj][m][n][1]);
;             o.y = pack2(bflo(ga.y) * acc[ai][bj][m][n][2], bfhi(ga.y) * acc[ai][bj][m][n][3]);
;             *(uint2*)(M + token * 1024 + f) = o;
	s_waitcnt lgkmcnt(0)
	s_setprio 1
	s_waitcnt lgkmcnt(0)
	v_mfma_f32_16x16x32_bf16 v[62:65], v[138:141], v[182:185], v[62:65]
	v_mfma_f32_16x16x32_bf16 v[58:61], v[174:177], v[182:185], v[58:61]
	v_mfma_f32_16x16x32_bf16 v[50:53], v[138:141], v[190:193], v[50:53]
	v_mfma_f32_16x16x32_bf16 v[42:45], v[174:177], v[190:193], v[42:45]
	v_mfma_f32_16x16x32_bf16 v[30:33], v[138:141], v[198:201], v[30:33]
	v_mfma_f32_16x16x32_bf16 v[26:29], v[174:177], v[198:201], v[26:29]
	v_mfma_f32_16x16x32_bf16 v[14:17], v[138:141], v[206:209], v[14:17]
	v_mfma_f32_16x16x32_bf16 v[10:13], v[174:177], v[206:209], v[10:13]
	v_mfma_f32_16x16x32_bf16 v[62:65], v[142:145], v[186:189], v[62:65]
	v_mfma_f32_16x16x32_bf16 v[58:61], v[178:181], v[186:189], v[58:61]
	v_mfma_f32_16x16x32_bf16 v[50:53], v[142:145], v[194:197], v[50:53]
	v_mfma_f32_16x16x32_bf16 v[42:45], v[178:181], v[194:197], v[42:45]
	v_mfma_f32_16x16x32_bf16 v[30:33], v[142:145], v[202:205], v[30:33]
	v_mfma_f32_16x16x32_bf16 v[26:29], v[178:181], v[202:205], v[26:29]
	v_mfma_f32_16x16x32_bf16 v[14:17], v[142:145], v[210:213], v[14:17]
	v_mfma_f32_16x16x32_bf16 v[10:13], v[178:181], v[210:213], v[10:13]
	s_setprio 0
	s_barrier
	s_add_u32 s30, s30, 0x20080
	s_addc_u32 s31, s31, 0
	s_mov_b32 m0, s50
	v_lshl_add_u64 v[138:139], s[30:31], 0, v[130:131]
	global_load_lds_dwordx4 v[138:139], off
	v_lshl_add_u64 v[138:139], s[30:31], 0, v[132:133]
	s_mov_b32 m0, s51
	s_nop 0
	global_load_lds_dwordx4 v[138:139], off
	s_waitcnt vmcnt(6)
	s_barrier
	s_setprio 1
	v_mfma_f32_16x16x32_bf16 v[54:57], v[214:217], v[182:185], v[54:57]
	v_mfma_f32_16x16x32_bf16 v[46:49], v[222:225], v[182:185], v[46:49]
	v_mfma_f32_16x16x32_bf16 v[38:41], v[214:217], v[190:193], v[38:41]
	v_mfma_f32_16x16x32_bf16 v[34:37], v[222:225], v[190:193], v[34:37]
	v_mfma_f32_16x16x32_bf16 v[22:25], v[214:217], v[198:201], v[22:25]
	v_mfma_f32_16x16x32_bf16 v[18:21], v[222:225], v[198:201], v[18:21]
	v_mfma_f32_16x16x32_bf16 v[6:9], v[214:217], v[206:209], v[6:9]
	v_mfma_f32_16x16x32_bf16 v[2:5], v[222:225], v[206:209], v[2:5]
	v_mfma_f32_16x16x32_bf16 v[54:57], v[218:221], v[186:189], v[54:57]
	v_mfma_f32_16x16x32_bf16 v[46:49], v[226:229], v[186:189], v[46:49]
	v_mfma_f32_16x16x32_bf16 v[38:41], v[218:221], v[194:197], v[38:41]
	v_mfma_f32_16x16x32_bf16 v[34:37], v[226:229], v[194:197], v[34:37]
	v_mfma_f32_16x16x32_bf16 v[22:25], v[218:221], v[202:205], v[22:25]
	v_mfma_f32_16x16x32_bf16 v[18:21], v[226:229], v[202:205], v[18:21]
	v_mfma_f32_16x16x32_bf16 v[6:9], v[218:221], v[210:213], v[6:9]
	v_mfma_f32_16x16x32_bf16 v[2:5], v[226:229], v[210:213], v[2:5]
	s_setprio 0
	s_add_i32 s63, s63, 2
	s_add_u32 s28, s28, 0x100
	s_addc_u32 s29, s29, 0
	s_add_u32 s61, s61, 0x100
	s_addc_u32 s62, s62, 0
	s_cmp_gt_u32 s63, 5
	s_barrier
	s_cbranch_scc0 .LBB0_694
	v_lshl_add_u32 v138, s26, 8, v154
	v_lshl_or_b32 v140, s24, 8, v156
	v_ashrrev_i32_e32 v139, 31, v138
	v_ashrrev_i32_e32 v141, 31, v140
	v_lshlrev_b64 v[142:143], 11, v[138:139]
	v_lshlrev_b64 v[140:141], 1, v[140:141]
	v_bfe_u32 v144, v0, 4, 1
	v_mov_b32_e32 v145, 0
	v_mul_u32_u24_e32 v144, 24, v144
	v_lshl_add_u64 v[142:143], v[142:143], 0, v[140:141]
	v_lshl_add_u64 v[142:143], v[142:143], 0, v[144:145]
	v_lshl_add_u64 v[232:233], s[10:11], 0, v[142:143]
	v_lshl_add_u64 v[236:237], s[12:13], 0, v[142:143]
	s_mov_b32 s24, s14
	s_mov_b32 s26, s16
	s_mov_b64 s[30:31], s[22:23]
	s_mov_b64 s[28:29], s[20:21]
	global_load_dwordx4 v[176:179], v[232:233], off
	global_load_dwordx4 v[180:183], v[232:233], off offset:256
	v_permlane16_swap_b32_e32 v126, v122
	v_permlane16_swap_b32_e32 v127, v123
	v_permlane16_swap_b32_e32 v128, v124
	v_permlane16_swap_b32_e32 v129, v125
	v_permlane16_swap_b32_e32 v114, v110
	v_permlane16_swap_b32_e32 v115, v111
	v_permlane16_swap_b32_e32 v116, v112
	v_permlane16_swap_b32_e32 v117, v113
	s_mov_b64 s[4:5], 0x8000
	v_lshl_add_u64 v[232:233], v[232:233], 0, s[4:5]
	global_load_dwordx4 v[192:195], v[232:233], off
	global_load_dwordx4 v[196:199], v[232:233], off offset:256
	s_waitcnt vmcnt(2)
	v_lshlrev_b32_e32 v208, 16, v176
	v_and_b32_e32 v209, 0xffff0000, v176
	v_pk_mul_f32 v[126:127], v[126:127], v[208:209]
	v_lshlrev_b32_e32 v210, 16, v177
	v_and_b32_e32 v211, 0xffff0000, v177
	v_pk_mul_f32 v[128:129], v[128:129], v[210:211]
	v_lshlrev_b32_e32 v212, 16, v178
	v_and_b32_e32 v213, 0xffff0000, v178
	v_pk_mul_f32 v[122:123], v[122:123], v[212:213]
	v_lshlrev_b32_e32 v214, 16, v179
	v_and_b32_e32 v215, 0xffff0000, v179
	v_pk_mul_f32 v[124:125], v[124:125], v[214:215]
	v_cvt_pk_bf16_f32 v224, v126, v127
	v_cvt_pk_bf16_f32 v225, v128, v129
	v_cvt_pk_bf16_f32 v226, v122, v123
	v_cvt_pk_bf16_f32 v227, v124, v125
	v_lshlrev_b32_e32 v208, 16, v180
	v_and_b32_e32 v209, 0xffff0000, v180
	v_pk_mul_f32 v[114:115], v[114:115], v[208:209]
	v_lshlrev_b32_e32 v210, 16, v181
	v_and_b32_e32 v211, 0xffff0000, v181
	v_pk_mul_f32 v[116:117], v[116:117], v[210:211]
	v_lshlrev_b32_e32 v212, 16, v182
	v_and_b32_e32 v213, 0xffff0000, v182
	v_pk_mul_f32 v[110:111], v[110:111], v[212:213]
	v_lshlrev_b32_e32 v214, 16, v183
	v_and_b32_e32 v215, 0xffff0000, v183
	v_pk_mul_f32 v[112:113], v[112:113], v[214:215]
	v_cvt_pk_bf16_f32 v228, v114, v115
	v_cvt_pk_bf16_f32 v229, v116, v117
	v_cvt_pk_bf16_f32 v230, v110, v111
	v_cvt_pk_bf16_f32 v231, v112, v113
	global_store_dwordx4 v[236:237], v[224:227], off
	global_store_dwordx4 v[236:237], v[228:231], off offset:256
	v_lshl_add_u64 v[236:237], v[236:237], 0, s[4:5]
	v_permlane16_swap_b32_e32 v118, v106
	v_permlane16_swap_b32_e32 v119, v107
	v_permlane16_swap_b32_e32 v120, v108
	v_permlane16_swap_b32_e32 v121, v109
	v_permlane16_swap_b32_e32 v102, v90
	v_permlane16_swap_b32_e32 v103, v91
	v_permlane16_swap_b32_e32 v104, v92
	v_permlane16_swap_b32_e32 v105, v93
	s_mov_b64 s[4:5], 0x8000
	v_lshl_add_u64 v[232:233], v[232:233], 0, s[4:5]
	global_load_dwordx4 v[176:179], v[232:233], off
	global_load_dwordx4 v[180:183], v[232:233], off offset:256
	s_waitcnt vmcnt(4)
; __device__ __forceinline__ float bflo(uint32_t v) { return __uint_as_float(v << 16); }
; __device__ __forceinline__ float bfhi(uint32_t v) { return __uint_as_float(v & 0xFFFF0000u); }
;   __device__ __forceinline__ void operator()(const acc8_t& acc, const pg8::Unit& u, int wr, int wc, int fr, int fq) const {
;     const u16* GA = (const u16*)(ws + OFF_GA); u16* M = (u16*)(ws + OFF_M);
; #pragma unroll
;     for (int ai = 0; ai < 2; ai++)
; #pragma unroll
;       for (int m = 0; m < 4; m++) {
;         const size_t token = EPI_TOKEN(u, ai, m);
; #pragma unroll
;         for (int bj = 0; bj < 2; bj++)
; #pragma unroll
;           for (int n = 0; n < 2; n++) {
;             const int f = EPI_COL(u, bj, n);
;             const uint2 ga = *(const uint2*)(GA + token * 1024 + f);
;             uint2 o;
;             o.x = pack2(bflo(ga.x) * acc[ai][bj][m][n][0], bfhi(ga.x) * acc[ai][bj][m][n][1]);
;             o.y = pack2(bflo(ga.y) * acc[ai][bj][m][n][2], bfhi(ga.y) * acc[ai][bj][m][n][3]);
;             *(uint2*)(M + token * 1024 + f) = o;
;           }
;       }
	v_lshlrev_b32_e32 v208, 16, v192
	v_and_b32_e32 v209, 0xffff0000, v192
	v_pk_mul_f32 v[118:119], v[118:119], v[208:209]
	v_lshlrev_b32_e32 v210, 16, v193
	v_and_b32_e32 v211, 0xffff0000, v193
	v_pk_mul_f32 v[120:121], v[120:121], v[210:211]
	v_lshlrev_b32_e32 v212, 16, v194
	v_and_b32_e32 v213, 0xffff0000, v194
	v_pk_mul_f32 v[106:107], v[106:107], v[212:213]
	v_lshlrev_b32_e32 v214, 16, v195
	v_and_b32_e32 v215, 0xffff0000, v195
	v_pk_mul_f32 v[108:109], v[108:109], v[214:215]
	v_cvt_pk_bf16_f32 v224, v118, v119
	v_cvt_pk_bf16_f32 v225, v120, v121
	v_cvt_pk_bf16_f32 v226, v106, v107
	v_cvt_pk_bf16_f32 v227, v108, v109
	v_lshlrev_b32_e32 v208, 16, v196
	v_and_b32_e32 v209, 0xffff0000, v196
	v_pk_mul_f32 v[102:103], v[102:103], v[208:209]
	v_lshlrev_b32_e32 v210, 16, v197
	v_and_b32_e32 v211, 0xffff0000, v197
	v_pk_mul_f32 v[104:105], v[104:105], v[210:211]
	v_lshlrev_b32_e32 v212, 16, v198
	v_and_b32_e32 v213, 0xffff0000, v198
	v_pk_mul_f32 v[90:91], v[90:91], v[212:213]
	v_lshlrev_b32_e32 v214, 16, v199
	v_and_b32_e32 v215, 0xffff0000, v199
	v_pk_mul_f32 v[92:93], v[92:93], v[214:215]
	v_cvt_pk_bf16_f32 v228, v102, v103
	v_cvt_pk_bf16_f32 v229, v104, v105
	v_cvt_pk_bf16_f32 v230, v90, v91
	v_cvt_pk_bf16_f32 v231, v92, v93
	global_store_dwordx4 v[236:237], v[224:227], off
	global_store_dwordx4 v[236:237], v[228:231], off offset:256
	v_lshl_add_u64 v[236:237], v[236:237], 0, s[4:5]
	v_permlane16_swap_b32_e32 v98, v94
	v_permlane16_swap_b32_e32 v99, v95
	v_permlane16_swap_b32_e32 v100, v96
	v_permlane16_swap_b32_e32 v101, v97
	v_permlane16_swap_b32_e32 v82, v70
	v_permlane16_swap_b32_e32 v83, v71
	v_permlane16_swap_b32_e32 v84, v72
	v_permlane16_swap_b32_e32 v85, v73
	s_mov_b64 s[4:5], 0x8000
	v_lshl_add_u64 v[232:233], v[232:233], 0, s[4:5]
	global_load_dwordx4 v[192:195], v[232:233], off
	global_load_dwordx4 v[196:199], v[232:233], off offset:256
	s_waitcnt vmcnt(4)
	v_lshlrev_b32_e32 v208, 16, v176
	v_and_b32_e32 v209, 0xffff0000, v176
	v_pk_mul_f32 v[98:99], v[98:99], v[208:209]
	v_lshlrev_b32_e32 v210, 16, v177
	v_and_b32_e32 v211, 0xffff0000, v177
	v_pk_mul_f32 v[100:101], v[100:101], v[210:211]
	v_lshlrev_b32_e32 v212, 16, v178
	v_and_b32_e32 v213, 0xffff0000, v178
	v_pk_mul_f32 v[94:95], v[94:95], v[212:213]
	v_lshlrev_b32_e32 v214, 16, v179
	v_and_b32_e32 v215, 0xffff0000, v179
	v_pk_mul_f32 v[96:97], v[96:97], v[214:215]
	v_cvt_pk_bf16_f32 v224, v98, v99
	v_cvt_pk_bf16_f32 v225, v100, v101
	v_cvt_pk_bf16_f32 v226, v94, v95
	v_cvt_pk_bf16_f32 v227, v96, v97
	v_lshlrev_b32_e32 v208, 16, v180
	v_and_b32_e32 v209, 0xffff0000, v180
	v_pk_mul_f32 v[82:83], v[82:83], v[208:209]
	v_lshlrev_b32_e32 v210, 16, v181
	v_and_b32_e32 v211, 0xffff0000, v181
	v_pk_mul_f32 v[84:85], v[84:85], v[210:211]
	v_lshlrev_b32_e32 v212, 16, v182
	v_and_b32_e32 v213, 0xffff0000, v182
	v_pk_mul_f32 v[70:71], v[70:71], v[212:213]
	v_lshlrev_b32_e32 v214, 16, v183
	v_and_b32_e32 v215, 0xffff0000, v183
	v_pk_mul_f32 v[72:73], v[72:73], v[214:215]
	v_cvt_pk_bf16_f32 v228, v82, v83
	v_cvt_pk_bf16_f32 v229, v84, v85
	v_cvt_pk_bf16_f32 v230, v70, v71
	v_cvt_pk_bf16_f32 v231, v72, v73
	global_store_dwordx4 v[236:237], v[224:227], off
	global_store_dwordx4 v[236:237], v[228:231], off offset:256
	v_lshl_add_u64 v[236:237], v[236:237], 0, s[4:5]
	v_permlane16_swap_b32_e32 v86, v78
	v_permlane16_swap_b32_e32 v87, v79
	v_permlane16_swap_b32_e32 v88, v80
	v_permlane16_swap_b32_e32 v89, v81
	v_permlane16_swap_b32_e32 v74, v66
	v_permlane16_swap_b32_e32 v75, v67
	v_permlane16_swap_b32_e32 v76, v68
	v_permlane16_swap_b32_e32 v77, v69
	s_mov_b64 s[4:5], 0x28000
	v_lshl_add_u64 v[232:233], v[232:233], 0, s[4:5]
	global_load_dwordx4 v[176:179], v[232:233], off
	global_load_dwordx4 v[180:183], v[232:233], off offset:256
	s_waitcnt vmcnt(4)
	v_lshlrev_b32_e32 v208, 16, v192
	v_and_b32_e32 v209, 0xffff0000, v192
	v_pk_mul_f32 v[86:87], v[86:87], v[208:209]
	v_lshlrev_b32_e32 v210, 16, v193
	v_and_b32_e32 v211, 0xffff0000, v193
	v_pk_mul_f32 v[88:89], v[88:89], v[210:211]
	v_lshlrev_b32_e32 v212, 16, v194
	v_and_b32_e32 v213, 0xffff0000, v194
	v_pk_mul_f32 v[78:79], v[78:79], v[212:213]
	v_lshlrev_b32_e32 v214, 16, v195
	v_and_b32_e32 v215, 0xffff0000, v195
	v_pk_mul_f32 v[80:81], v[80:81], v[214:215]
	v_cvt_pk_bf16_f32 v224, v86, v87
	v_cvt_pk_bf16_f32 v225, v88, v89
	v_cvt_pk_bf16_f32 v226, v78, v79
	v_cvt_pk_bf16_f32 v227, v80, v81
	v_lshlrev_b32_e32 v208, 16, v196
	v_and_b32_e32 v209, 0xffff0000, v196
	v_pk_mul_f32 v[74:75], v[74:75], v[208:209]
	v_lshlrev_b32_e32 v210, 16, v197
	v_and_b32_e32 v211, 0xffff0000, v197
	v_pk_mul_f32 v[76:77], v[76:77], v[210:211]
	v_lshlrev_b32_e32 v212, 16, v198
	v_and_b32_e32 v213, 0xffff0000, v198
	v_pk_mul_f32 v[66:67], v[66:67], v[212:213]
	v_lshlrev_b32_e32 v214, 16, v199
	v_and_b32_e32 v215, 0xffff0000, v199
	v_pk_mul_f32 v[68:69], v[68:69], v[214:215]
	v_cvt_pk_bf16_f32 v228, v74, v75
	v_cvt_pk_bf16_f32 v229, v76, v77
	v_cvt_pk_bf16_f32 v230, v66, v67
	v_cvt_pk_bf16_f32 v231, v68, v69
	global_store_dwordx4 v[236:237], v[224:227], off
	global_store_dwordx4 v[236:237], v[228:231], off offset:256
	v_lshl_add_u64 v[236:237], v[236:237], 0, s[4:5]
	v_permlane16_swap_b32_e32 v62, v58
	v_permlane16_swap_b32_e32 v63, v59
	v_permlane16_swap_b32_e32 v64, v60
	v_permlane16_swap_b32_e32 v65, v61
	v_permlane16_swap_b32_e32 v54, v46
	v_permlane16_swap_b32_e32 v55, v47
	v_permlane16_swap_b32_e32 v56, v48
	v_permlane16_swap_b32_e32 v57, v49
	s_mov_b64 s[4:5], 0x8000
	v_lshl_add_u64 v[232:233], v[232:233], 0, s[4:5]
	global_load_dwordx4 v[192:195], v[232:233], off
	global_load_dwordx4 v[196:199], v[232:233], off offset:256
	s_waitcnt vmcnt(4)
; __device__ __forceinline__ float bflo(uint32_t v) { return __uint_as_float(v << 16); }
; __device__ __forceinline__ float bfhi(uint32_t v) { return __uint_as_float(v & 0xFFFF0000u); }
; #define PG8_WAIT_V(n) asm volatile("s_waitcnt vmcnt(" #n ")" ::: "memory")
; #define PG8_BAR __builtin_amdgcn_s_barrier()
; template <class Epi, class Sched>
; __device__ __forceinline__ void gemm_phase(PG8_LAS unsigned char* lds, const Gemm g, const Sched& S, const Epi& E) {
;     ...
;         E(acc, cur, wr, wc, fr, fq);
;         if (!has_next) break;
; #pragma unroll
;         for (int a = 0; a < 2; ++a)
; #pragma unroll
;             for (int b = 0; b < 2; ++b)
; #pragma unroll
;                 for (int m = 0; m < 4; ++m)
; #pragma unroll
;                     for (int n = 0; n < 2; ++n) acc[a][b][m][n] = (f32x4){0.f, 0.f, 0.f, 0.f};
;         cur = nxt; cA = nA; cB = nB; ++ui;
;     }
;     PG8_WAIT_V(0);
;     if (wr == 0) PG8_BAR;
;     PG8_BAR;
;   __device__ __forceinline__ void operator()(const acc8_t& acc, const pg8::Unit& u, int wr, int wc, int fr, int fq) const {
;     ...
; #pragma unroll
;     for (int ai = 0; ai < 2; ai++)
; #pragma unroll
;       for (int m = 0; m < 4; m++) {
;         const size_t token = EPI_TOKEN(u, ai, m);
; #pragma unroll
;         for (int bj = 0; bj < 2; bj++)
; #pragma unroll
;           for (int n = 0; n < 2; n++) {
;             const int f = EPI_COL(u, bj, n);
;             const uint2 ga = *(const uint2*)(GA + token * 1024 + f);
;             uint2 o;
;             o.x = pack2(bflo(ga.x) * acc[ai][bj][m][n][0], bfhi(ga.x) * acc[ai][bj][m][n][1]);
;             o.y = pack2(bflo(ga.y) * acc[ai][bj][m][n][2], bfhi(ga.y) * acc[ai][bj][m][n][3]);
;             *(uint2*)(M + token * 1024 + f) = o;
;           }
;       }
	v_lshlrev_b32_e32 v208, 16, v176
	v_and_b32_e32 v209, 0xffff0000, v176
	v_pk_mul_f32 v[62:63], v[62:63], v[208:209]
	v_lshlrev_b32_e32 v210, 16, v177
	v_and_b32_e32 v211, 0xffff0000, v177
	v_pk_mul_f32 v[64:65], v[64:65], v[210:211]
	v_lshlrev_b32_e32 v212, 16, v178
	v_and_b32_e32 v213, 0xffff0000, v178
	v_pk_mul_f32 v[58:59], v[58:59], v[212:213]
	v_lshlrev_b32_e32 v214, 16, v179
	v_and_b32_e32 v215, 0xffff0000, v179
	v_pk_mul_f32 v[60:61], v[60:61], v[214:215]
	v_cvt_pk_bf16_f32 v224, v62, v63
	v_cvt_pk_bf16_f32 v225, v64, v65
	v_cvt_pk_bf16_f32 v226, v58, v59
	v_cvt_pk_bf16_f32 v227, v60, v61
	v_lshlrev_b32_e32 v208, 16, v180
	v_and_b32_e32 v209, 0xffff0000, v180
	v_pk_mul_f32 v[54:55], v[54:55], v[208:209]
	v_lshlrev_b32_e32 v210, 16, v181
	v_and_b32_e32 v211, 0xffff0000, v181
	v_pk_mul_f32 v[56:57], v[56:57], v[210:211]
	v_lshlrev_b32_e32 v212, 16, v182
	v_and_b32_e32 v213, 0xffff0000, v182
	v_pk_mul_f32 v[46:47], v[46:47], v[212:213]
	v_lshlrev_b32_e32 v214, 16, v183
	v_and_b32_e32 v215, 0xffff0000, v183
	v_pk_mul_f32 v[48:49], v[48:49], v[214:215]
	v_cvt_pk_bf16_f32 v228, v54, v55
	v_cvt_pk_bf16_f32 v229, v56, v57
	v_cvt_pk_bf16_f32 v230, v46, v47
	v_cvt_pk_bf16_f32 v231, v48, v49
	global_store_dwordx4 v[236:237], v[224:227], off
	global_store_dwordx4 v[236:237], v[228:231], off offset:256
	v_lshl_add_u64 v[236:237], v[236:237], 0, s[4:5]
	v_permlane16_swap_b32_e32 v50, v42
	v_permlane16_swap_b32_e32 v51, v43
	v_permlane16_swap_b32_e32 v52, v44
	v_permlane16_swap_b32_e32 v53, v45
	v_permlane16_swap_b32_e32 v38, v34
	v_permlane16_swap_b32_e32 v39, v35
	v_permlane16_swap_b32_e32 v40, v36
	v_permlane16_swap_b32_e32 v41, v37
	s_mov_b64 s[4:5], 0x8000
	v_lshl_add_u64 v[232:233], v[232:233], 0, s[4:5]
	global_load_dwordx4 v[176:179], v[232:233], off
	global_load_dwordx4 v[180:183], v[232:233], off offset:256
	s_waitcnt vmcnt(4)
	v_lshlrev_b32_e32 v208, 16, v192
	v_and_b32_e32 v209, 0xffff0000, v192
	v_pk_mul_f32 v[50:51], v[50:51], v[208:209]
	v_lshlrev_b32_e32 v210, 16, v193
	v_and_b32_e32 v211, 0xffff0000, v193
	v_pk_mul_f32 v[52:53], v[52:53], v[210:211]
	v_lshlrev_b32_e32 v212, 16, v194
	v_and_b32_e32 v213, 0xffff0000, v194
	v_pk_mul_f32 v[42:43], v[42:43], v[212:213]
	v_lshlrev_b32_e32 v214, 16, v195
	v_and_b32_e32 v215, 0xffff0000, v195
	v_pk_mul_f32 v[44:45], v[44:45], v[214:215]
	v_cvt_pk_bf16_f32 v224, v50, v51
	v_cvt_pk_bf16_f32 v225, v52, v53
	v_cvt_pk_bf16_f32 v226, v42, v43
	v_cvt_pk_bf16_f32 v227, v44, v45
	v_lshlrev_b32_e32 v208, 16, v196
	v_and_b32_e32 v209, 0xffff0000, v196
	v_pk_mul_f32 v[38:39], v[38:39], v[208:209]
	v_lshlrev_b32_e32 v210, 16, v197
	v_and_b32_e32 v211, 0xffff0000, v197
	v_pk_mul_f32 v[40:41], v[40:41], v[210:211]
	v_lshlrev_b32_e32 v212, 16, v198
	v_and_b32_e32 v213, 0xffff0000, v198
	v_pk_mul_f32 v[34:35], v[34:35], v[212:213]
	v_lshlrev_b32_e32 v214, 16, v199
	v_and_b32_e32 v215, 0xffff0000, v199
	v_pk_mul_f32 v[36:37], v[36:37], v[214:215]
	v_cvt_pk_bf16_f32 v228, v38, v39
	v_cvt_pk_bf16_f32 v229, v40, v41
	v_cvt_pk_bf16_f32 v230, v34, v35
	v_cvt_pk_bf16_f32 v231, v36, v37
	global_store_dwordx4 v[236:237], v[224:227], off
	global_store_dwordx4 v[236:237], v[228:231], off offset:256
	v_lshl_add_u64 v[236:237], v[236:237], 0, s[4:5]
	v_permlane16_swap_b32_e32 v30, v26
	v_permlane16_swap_b32_e32 v31, v27
	v_permlane16_swap_b32_e32 v32, v28
	v_permlane16_swap_b32_e32 v33, v29
	v_permlane16_swap_b32_e32 v22, v18
	v_permlane16_swap_b32_e32 v23, v19
	v_permlane16_swap_b32_e32 v24, v20
	v_permlane16_swap_b32_e32 v25, v21
	s_mov_b64 s[4:5], 0x8000
	v_lshl_add_u64 v[232:233], v[232:233], 0, s[4:5]
	global_load_dwordx4 v[192:195], v[232:233], off
	global_load_dwordx4 v[196:199], v[232:233], off offset:256
	s_waitcnt vmcnt(4)
	v_lshlrev_b32_e32 v208, 16, v176
	v_and_b32_e32 v209, 0xffff0000, v176
	v_pk_mul_f32 v[30:31], v[30:31], v[208:209]
	v_lshlrev_b32_e32 v210, 16, v177
	v_and_b32_e32 v211, 0xffff0000, v177
	v_pk_mul_f32 v[32:33], v[32:33], v[210:211]
	v_lshlrev_b32_e32 v212, 16, v178
	v_and_b32_e32 v213, 0xffff0000, v178
	v_pk_mul_f32 v[26:27], v[26:27], v[212:213]
	v_lshlrev_b32_e32 v214, 16, v179
	v_and_b32_e32 v215, 0xffff0000, v179
	v_pk_mul_f32 v[28:29], v[28:29], v[214:215]
	v_cvt_pk_bf16_f32 v224, v30, v31
	v_cvt_pk_bf16_f32 v225, v32, v33
	v_cvt_pk_bf16_f32 v226, v26, v27
	v_cvt_pk_bf16_f32 v227, v28, v29
	v_lshlrev_b32_e32 v208, 16, v180
	v_and_b32_e32 v209, 0xffff0000, v180
	v_pk_mul_f32 v[22:23], v[22:23], v[208:209]
	v_lshlrev_b32_e32 v210, 16, v181
	v_and_b32_e32 v211, 0xffff0000, v181
	v_pk_mul_f32 v[24:25], v[24:25], v[210:211]
	v_lshlrev_b32_e32 v212, 16, v182
	v_and_b32_e32 v213, 0xffff0000, v182
	v_pk_mul_f32 v[18:19], v[18:19], v[212:213]
	v_lshlrev_b32_e32 v214, 16, v183
	v_and_b32_e32 v215, 0xffff0000, v183
	v_pk_mul_f32 v[20:21], v[20:21], v[214:215]
	v_cvt_pk_bf16_f32 v228, v22, v23
	v_cvt_pk_bf16_f32 v229, v24, v25
	v_cvt_pk_bf16_f32 v230, v18, v19
	v_cvt_pk_bf16_f32 v231, v20, v21
	global_store_dwordx4 v[236:237], v[224:227], off
	global_store_dwordx4 v[236:237], v[228:231], off offset:256
	v_lshl_add_u64 v[236:237], v[236:237], 0, s[4:5]
	v_permlane16_swap_b32_e32 v14, v10
	v_permlane16_swap_b32_e32 v15, v11
	v_permlane16_swap_b32_e32 v16, v12
	v_permlane16_swap_b32_e32 v17, v13
	v_permlane16_swap_b32_e32 v6, v2
	v_permlane16_swap_b32_e32 v7, v3
	v_permlane16_swap_b32_e32 v8, v4
	v_permlane16_swap_b32_e32 v9, v5
	s_waitcnt vmcnt(2)
	v_lshlrev_b32_e32 v208, 16, v192
	v_and_b32_e32 v209, 0xffff0000, v192
	v_pk_mul_f32 v[14:15], v[14:15], v[208:209]
	v_lshlrev_b32_e32 v210, 16, v193
	v_and_b32_e32 v211, 0xffff0000, v193
	v_pk_mul_f32 v[16:17], v[16:17], v[210:211]
	v_lshlrev_b32_e32 v212, 16, v194
	v_and_b32_e32 v213, 0xffff0000, v194
	v_pk_mul_f32 v[10:11], v[10:11], v[212:213]
	v_lshlrev_b32_e32 v214, 16, v195
	v_and_b32_e32 v215, 0xffff0000, v195
	v_pk_mul_f32 v[12:13], v[12:13], v[214:215]
	v_cvt_pk_bf16_f32 v224, v14, v15
	v_cvt_pk_bf16_f32 v225, v16, v17
	v_cvt_pk_bf16_f32 v226, v10, v11
	v_cvt_pk_bf16_f32 v227, v12, v13
	v_lshlrev_b32_e32 v208, 16, v196
	v_and_b32_e32 v209, 0xffff0000, v196
	v_pk_mul_f32 v[6:7], v[6:7], v[208:209]
	v_lshlrev_b32_e32 v210, 16, v197
	v_and_b32_e32 v211, 0xffff0000, v197
	v_pk_mul_f32 v[8:9], v[8:9], v[210:211]
	v_lshlrev_b32_e32 v212, 16, v198
	v_and_b32_e32 v213, 0xffff0000, v198
	v_pk_mul_f32 v[2:3], v[2:3], v[212:213]
	v_lshlrev_b32_e32 v214, 16, v199
	v_and_b32_e32 v215, 0xffff0000, v199
	v_pk_mul_f32 v[4:5], v[4:5], v[214:215]
	v_cvt_pk_bf16_f32 v228, v6, v7
	v_cvt_pk_bf16_f32 v229, v8, v9
	v_cvt_pk_bf16_f32 v230, v2, v3
	v_cvt_pk_bf16_f32 v231, v4, v5
	global_store_dwordx4 v[236:237], v[224:227], off
	global_store_dwordx4 v[236:237], v[228:231], off offset:256
	s_and_b64 vcc, exec, s[18:19]
	s_cbranch_vccz .LBB0_688
	s_waitcnt vmcnt(0)
	s_cmpk_gt_u32 s33, 0xff
	s_cbranch_scc1 .LBB0_698
	s_barrier

; __device__ __forceinline__ float bflo(uint32_t v) { return __uint_as_float(v << 16); }
; __device__ __forceinline__ float bfhi(uint32_t v) { return __uint_as_float(v & 0xFFFF0000u); }
;   __device__ __forceinline__ void operator()(const acc8_t& acc, const pg8::Unit& u, int wr, int wc, int fr, int fq) const {
;     const u16* GB = (const u16*)(ws + OFF_GB); u16* M = (u16*)(ws + OFF_M);
; #pragma unroll
;     for (int ai = 0; ai < 2; ai++)
; #pragma unroll
;       for (int m = 0; m < 4; m++) {
;         const size_t token = EPI_TOKEN(u, ai, m);
; #pragma unroll
;         for (int bj = 0; bj < 2; bj++)
; #pragma unroll
;           for (int n = 0; n < 2; n++) {
;             const int f = EPI_COL(u, bj, n);
;             const uint2 gb = *(const uint2*)(GB + token * 1024 + f);
;             const uint2 mo = *(const uint2*)(M + token * 1024 + f);
;             uint2 o;
;             o.x = pack2(bflo(mo.x) + bflo(gb.x) * acc[ai][bj][m][n][0], bfhi(mo.x) + bfhi(gb.x) * acc[ai][bj][m][n][1]);
;             o.y = pack2(bflo(mo.y) + bflo(gb.y) * acc[ai][bj][m][n][2], bfhi(mo.y) + bfhi(gb.y) * acc[ai][bj][m][n][3]);
;             *(uint2*)(M + token * 1024 + f) = o;
.Lp4r_go:
	v_lshl_add_u32 v138, s24, 8, v154
	v_lshl_or_b32 v140, s22, 8, v156
	v_ashrrev_i32_e32 v139, 31, v138
	v_ashrrev_i32_e32 v141, 31, v140
	v_lshlrev_b64 v[142:143], 11, v[138:139]
	v_lshlrev_b64 v[140:141], 1, v[140:141]
	v_bfe_u32 v144, v0, 4, 1
	v_mov_b32_e32 v145, 0
	v_mul_u32_u24_e32 v144, 24, v144
	v_lshl_add_u64 v[142:143], v[142:143], 0, v[140:141]
	v_lshl_add_u64 v[142:143], v[142:143], 0, v[144:145]
	v_lshl_add_u64 v[232:233], s[8:9], 0, v[142:143]
	v_lshl_add_u64 v[236:237], s[10:11], 0, v[142:143]
	v_lshl_add_u64 v[234:235], s[10:11], 0, v[142:143]
	s_mov_b32 s22, s12
	s_mov_b32 s24, s14
	s_mov_b64 s[28:29], s[20:21]
	s_mov_b64 s[26:27], s[18:19]
	global_load_dwordx4 v[176:179], v[232:233], off
	global_load_dwordx4 v[180:183], v[232:233], off offset:256
	global_load_dwordx4 v[184:187], v[234:235], off
	global_load_dwordx4 v[188:191], v[234:235], off offset:256
	v_permlane16_swap_b32_e32 v126, v122
	v_permlane16_swap_b32_e32 v127, v123
	v_permlane16_swap_b32_e32 v128, v124
	v_permlane16_swap_b32_e32 v129, v125
	v_permlane16_swap_b32_e32 v118, v114
	v_permlane16_swap_b32_e32 v119, v115
	v_permlane16_swap_b32_e32 v120, v116
	v_permlane16_swap_b32_e32 v121, v117
	s_mov_b64 s[4:5], 0x8000
	v_lshl_add_u64 v[232:233], v[232:233], 0, s[4:5]
	v_lshl_add_u64 v[234:235], v[234:235], 0, s[4:5]
	global_load_dwordx4 v[192:195], v[232:233], off
	global_load_dwordx4 v[196:199], v[232:233], off offset:256
	global_load_dwordx4 v[200:203], v[234:235], off
	global_load_dwordx4 v[204:207], v[234:235], off offset:256
	s_waitcnt vmcnt(4)
	v_lshlrev_b32_e32 v208, 16, v176
	v_and_b32_e32 v209, 0xffff0000, v176
	v_lshlrev_b32_e32 v216, 16, v184
	v_and_b32_e32 v217, 0xffff0000, v184
	v_pk_fma_f32 v[126:127], v[126:127], v[208:209], v[216:217]
	v_lshlrev_b32_e32 v210, 16, v177
	v_and_b32_e32 v211, 0xffff0000, v177
	v_lshlrev_b32_e32 v218, 16, v185
	v_and_b32_e32 v219, 0xffff0000, v185
	v_pk_fma_f32 v[128:129], v[128:129], v[210:211], v[218:219]
	v_lshlrev_b32_e32 v212, 16, v178
	v_and_b32_e32 v213, 0xffff0000, v178
	v_lshlrev_b32_e32 v220, 16, v186
	v_and_b32_e32 v221, 0xffff0000, v186
	v_pk_fma_f32 v[122:123], v[122:123], v[212:213], v[220:221]
	v_lshlrev_b32_e32 v214, 16, v179
	v_and_b32_e32 v215, 0xffff0000, v179
	v_lshlrev_b32_e32 v222, 16, v187
	v_and_b32_e32 v223, 0xffff0000, v187
	v_pk_fma_f32 v[124:125], v[124:125], v[214:215], v[222:223]
	v_cvt_pk_bf16_f32 v224, v126, v127
	v_cvt_pk_bf16_f32 v225, v128, v129
	v_cvt_pk_bf16_f32 v226, v122, v123
	v_cvt_pk_bf16_f32 v227, v124, v125
	v_lshlrev_b32_e32 v208, 16, v180
	v_and_b32_e32 v209, 0xffff0000, v180
	v_lshlrev_b32_e32 v216, 16, v188
	v_and_b32_e32 v217, 0xffff0000, v188
	v_pk_fma_f32 v[118:119], v[118:119], v[208:209], v[216:217]
	v_lshlrev_b32_e32 v210, 16, v181
	v_and_b32_e32 v211, 0xffff0000, v181
	v_lshlrev_b32_e32 v218, 16, v189
	v_and_b32_e32 v219, 0xffff0000, v189
	v_pk_fma_f32 v[120:121], v[120:121], v[210:211], v[218:219]
	v_lshlrev_b32_e32 v212, 16, v182
	v_and_b32_e32 v213, 0xffff0000, v182
	v_lshlrev_b32_e32 v220, 16, v190
	v_and_b32_e32 v221, 0xffff0000, v190
	v_pk_fma_f32 v[114:115], v[114:115], v[212:213], v[220:221]
	v_lshlrev_b32_e32 v214, 16, v183
	v_and_b32_e32 v215, 0xffff0000, v183
	v_lshlrev_b32_e32 v222, 16, v191
	v_and_b32_e32 v223, 0xffff0000, v191
	v_pk_fma_f32 v[116:117], v[116:117], v[214:215], v[222:223]
	v_cvt_pk_bf16_f32 v228, v118, v119
	v_cvt_pk_bf16_f32 v229, v120, v121
	v_cvt_pk_bf16_f32 v230, v114, v115
	v_cvt_pk_bf16_f32 v231, v116, v117
	global_store_dwordx4 v[236:237], v[224:227], off
	global_store_dwordx4 v[236:237], v[228:231], off offset:256
	v_lshl_add_u64 v[236:237], v[236:237], 0, s[4:5]
	v_permlane16_swap_b32_e32 v110, v106
	v_permlane16_swap_b32_e32 v111, v107
	v_permlane16_swap_b32_e32 v112, v108
	v_permlane16_swap_b32_e32 v113, v109
	v_permlane16_swap_b32_e32 v102, v94
	v_permlane16_swap_b32_e32 v103, v95
	v_permlane16_swap_b32_e32 v104, v96
	v_permlane16_swap_b32_e32 v105, v97
	s_mov_b64 s[4:5], 0x8000
	v_lshl_add_u64 v[232:233], v[232:233], 0, s[4:5]
	v_lshl_add_u64 v[234:235], v[234:235], 0, s[4:5]
	global_load_dwordx4 v[176:179], v[232:233], off
	global_load_dwordx4 v[180:183], v[232:233], off offset:256
	global_load_dwordx4 v[184:187], v[234:235], off
	global_load_dwordx4 v[188:191], v[234:235], off offset:256
	s_waitcnt vmcnt(6)
; __device__ __forceinline__ float bflo(uint32_t v) { return __uint_as_float(v << 16); }
; __device__ __forceinline__ float bfhi(uint32_t v) { return __uint_as_float(v & 0xFFFF0000u); }
;   __device__ __forceinline__ void operator()(const acc8_t& acc, const pg8::Unit& u, int wr, int wc, int fr, int fq) const {
;     ...
;       for (int m = 0; m < 4; m++) {
;         const size_t token = EPI_TOKEN(u, ai, m);
; #pragma unroll
;         for (int bj = 0; bj < 2; bj++)
; #pragma unroll
;           for (int n = 0; n < 2; n++) {
;             const int f = EPI_COL(u, bj, n);
;             const uint2 gb = *(const uint2*)(GB + token * 1024 + f);
;             const uint2 mo = *(const uint2*)(M + token * 1024 + f);
;             uint2 o;
;             o.x = pack2(bflo(mo.x) + bflo(gb.x) * acc[ai][bj][m][n][0], bfhi(mo.x) + bfhi(gb.x) * acc[ai][bj][m][n][1]);
;             o.y = pack2(bflo(mo.y) + bflo(gb.y) * acc[ai][bj][m][n][2], bfhi(mo.y) + bfhi(gb.y) * acc[ai][bj][m][n][3]);
;             *(uint2*)(M + token * 1024 + f) = o;
	v_lshlrev_b32_e32 v208, 16, v192
	v_and_b32_e32 v209, 0xffff0000, v192
	v_lshlrev_b32_e32 v216, 16, v200
	v_and_b32_e32 v217, 0xffff0000, v200
	v_pk_fma_f32 v[110:111], v[110:111], v[208:209], v[216:217]
	v_lshlrev_b32_e32 v210, 16, v193
	v_and_b32_e32 v211, 0xffff0000, v193
	v_lshlrev_b32_e32 v218, 16, v201
	v_and_b32_e32 v219, 0xffff0000, v201
	v_pk_fma_f32 v[112:113], v[112:113], v[210:211], v[218:219]
	v_lshlrev_b32_e32 v212, 16, v194
	v_and_b32_e32 v213, 0xffff0000, v194
	v_lshlrev_b32_e32 v220, 16, v202
	v_and_b32_e32 v221, 0xffff0000, v202
	v_pk_fma_f32 v[106:107], v[106:107], v[212:213], v[220:221]
	v_lshlrev_b32_e32 v214, 16, v195
	v_and_b32_e32 v215, 0xffff0000, v195
	v_lshlrev_b32_e32 v222, 16, v203
	v_and_b32_e32 v223, 0xffff0000, v203
	v_pk_fma_f32 v[108:109], v[108:109], v[214:215], v[222:223]
	v_cvt_pk_bf16_f32 v224, v110, v111
	v_cvt_pk_bf16_f32 v225, v112, v113
	v_cvt_pk_bf16_f32 v226, v106, v107
	v_cvt_pk_bf16_f32 v227, v108, v109
	v_lshlrev_b32_e32 v208, 16, v196
	v_and_b32_e32 v209, 0xffff0000, v196
	v_lshlrev_b32_e32 v216, 16, v204
	v_and_b32_e32 v217, 0xffff0000, v204
	v_pk_fma_f32 v[102:103], v[102:103], v[208:209], v[216:217]
	v_lshlrev_b32_e32 v210, 16, v197
	v_and_b32_e32 v211, 0xffff0000, v197
	v_lshlrev_b32_e32 v218, 16, v205
	v_and_b32_e32 v219, 0xffff0000, v205
	v_pk_fma_f32 v[104:105], v[104:105], v[210:211], v[218:219]
	v_lshlrev_b32_e32 v212, 16, v198
	v_and_b32_e32 v213, 0xffff0000, v198
	v_lshlrev_b32_e32 v220, 16, v206
	v_and_b32_e32 v221, 0xffff0000, v206
	v_pk_fma_f32 v[94:95], v[94:95], v[212:213], v[220:221]
	v_lshlrev_b32_e32 v214, 16, v199
	v_and_b32_e32 v215, 0xffff0000, v199
	v_lshlrev_b32_e32 v222, 16, v207
	v_and_b32_e32 v223, 0xffff0000, v207
	v_pk_fma_f32 v[96:97], v[96:97], v[214:215], v[222:223]
	v_cvt_pk_bf16_f32 v228, v102, v103
	v_cvt_pk_bf16_f32 v229, v104, v105
	v_cvt_pk_bf16_f32 v230, v94, v95
	v_cvt_pk_bf16_f32 v231, v96, v97
	global_store_dwordx4 v[236:237], v[224:227], off
	global_store_dwordx4 v[236:237], v[228:231], off offset:256
	v_lshl_add_u64 v[236:237], v[236:237], 0, s[4:5]
	v_permlane16_swap_b32_e32 v98, v90
	v_permlane16_swap_b32_e32 v99, v91
	v_permlane16_swap_b32_e32 v100, v92
	v_permlane16_swap_b32_e32 v101, v93
	v_permlane16_swap_b32_e32 v78, v74
	v_permlane16_swap_b32_e32 v79, v75
	v_permlane16_swap_b32_e32 v80, v76
	v_permlane16_swap_b32_e32 v81, v77
	s_mov_b64 s[4:5], 0x8000
	v_lshl_add_u64 v[232:233], v[232:233], 0, s[4:5]
	v_lshl_add_u64 v[234:235], v[234:235], 0, s[4:5]
	global_load_dwordx4 v[192:195], v[232:233], off
	global_load_dwordx4 v[196:199], v[232:233], off offset:256
	global_load_dwordx4 v[200:203], v[234:235], off
	global_load_dwordx4 v[204:207], v[234:235], off offset:256
	s_waitcnt vmcnt(6)
	v_lshlrev_b32_e32 v208, 16, v176
	v_and_b32_e32 v209, 0xffff0000, v176
	v_lshlrev_b32_e32 v216, 16, v184
	v_and_b32_e32 v217, 0xffff0000, v184
	v_pk_fma_f32 v[98:99], v[98:99], v[208:209], v[216:217]
	v_lshlrev_b32_e32 v210, 16, v177
	v_and_b32_e32 v211, 0xffff0000, v177
	v_lshlrev_b32_e32 v218, 16, v185
	v_and_b32_e32 v219, 0xffff0000, v185
	v_pk_fma_f32 v[100:101], v[100:101], v[210:211], v[218:219]
	v_lshlrev_b32_e32 v212, 16, v178
	v_and_b32_e32 v213, 0xffff0000, v178
	v_lshlrev_b32_e32 v220, 16, v186
	v_and_b32_e32 v221, 0xffff0000, v186
	v_pk_fma_f32 v[90:91], v[90:91], v[212:213], v[220:221]
	v_lshlrev_b32_e32 v214, 16, v179
	v_and_b32_e32 v215, 0xffff0000, v179
	v_lshlrev_b32_e32 v222, 16, v187
	v_and_b32_e32 v223, 0xffff0000, v187
	v_pk_fma_f32 v[92:93], v[92:93], v[214:215], v[222:223]
	v_cvt_pk_bf16_f32 v224, v98, v99
	v_cvt_pk_bf16_f32 v225, v100, v101
	v_cvt_pk_bf16_f32 v226, v90, v91
	v_cvt_pk_bf16_f32 v227, v92, v93
	v_lshlrev_b32_e32 v208, 16, v180
	v_and_b32_e32 v209, 0xffff0000, v180
	v_lshlrev_b32_e32 v216, 16, v188
	v_and_b32_e32 v217, 0xffff0000, v188
	v_pk_fma_f32 v[78:79], v[78:79], v[208:209], v[216:217]
	v_lshlrev_b32_e32 v210, 16, v181
	v_and_b32_e32 v211, 0xffff0000, v181
	v_lshlrev_b32_e32 v218, 16, v189
	v_and_b32_e32 v219, 0xffff0000, v189
	v_pk_fma_f32 v[80:81], v[80:81], v[210:211], v[218:219]
	v_lshlrev_b32_e32 v212, 16, v182
	v_and_b32_e32 v213, 0xffff0000, v182
	v_lshlrev_b32_e32 v220, 16, v190
	v_and_b32_e32 v221, 0xffff0000, v190
	v_pk_fma_f32 v[74:75], v[74:75], v[212:213], v[220:221]
	v_lshlrev_b32_e32 v214, 16, v183
	v_and_b32_e32 v215, 0xffff0000, v183
	v_lshlrev_b32_e32 v222, 16, v191
	v_and_b32_e32 v223, 0xffff0000, v191
	v_pk_fma_f32 v[76:77], v[76:77], v[214:215], v[222:223]
	v_cvt_pk_bf16_f32 v228, v78, v79
	v_cvt_pk_bf16_f32 v229, v80, v81
	v_cvt_pk_bf16_f32 v230, v74, v75
	v_cvt_pk_bf16_f32 v231, v76, v77
	global_store_dwordx4 v[236:237], v[224:227], off
	global_store_dwordx4 v[236:237], v[228:231], off offset:256
	v_lshl_add_u64 v[236:237], v[236:237], 0, s[4:5]
	v_permlane16_swap_b32_e32 v86, v82
	v_permlane16_swap_b32_e32 v87, v83
	v_permlane16_swap_b32_e32 v88, v84
	v_permlane16_swap_b32_e32 v89, v85
	v_permlane16_swap_b32_e32 v70, v66
	v_permlane16_swap_b32_e32 v71, v67
	v_permlane16_swap_b32_e32 v72, v68
	v_permlane16_swap_b32_e32 v73, v69
	s_mov_b64 s[4:5], 0x28000
	v_lshl_add_u64 v[232:233], v[232:233], 0, s[4:5]
	v_lshl_add_u64 v[234:235], v[234:235], 0, s[4:5]
	global_load_dwordx4 v[176:179], v[232:233], off
	global_load_dwordx4 v[180:183], v[232:233], off offset:256
	global_load_dwordx4 v[184:187], v[234:235], off
	global_load_dwordx4 v[188:191], v[234:235], off offset:256
	s_waitcnt vmcnt(6)
; __device__ __forceinline__ float bflo(uint32_t v) { return __uint_as_float(v << 16); }
; __device__ __forceinline__ float bfhi(uint32_t v) { return __uint_as_float(v & 0xFFFF0000u); }
;   __device__ __forceinline__ void operator()(const acc8_t& acc, const pg8::Unit& u, int wr, int wc, int fr, int fq) const {
;     ...
;       for (int m = 0; m < 4; m++) {
;         const size_t token = EPI_TOKEN(u, ai, m);
; #pragma unroll
;         for (int bj = 0; bj < 2; bj++)
; #pragma unroll
;           for (int n = 0; n < 2; n++) {
;             const int f = EPI_COL(u, bj, n);
;             const uint2 gb = *(const uint2*)(GB + token * 1024 + f);
;             const uint2 mo = *(const uint2*)(M + token * 1024 + f);
;             uint2 o;
;             o.x = pack2(bflo(mo.x) + bflo(gb.x) * acc[ai][bj][m][n][0], bfhi(mo.x) + bfhi(gb.x) * acc[ai][bj][m][n][1]);
;             o.y = pack2(bflo(mo.y) + bflo(gb.y) * acc[ai][bj][m][n][2], bfhi(mo.y) + bfhi(gb.y) * acc[ai][bj][m][n][3]);
;             *(uint2*)(M + token * 1024 + f) = o;
	v_lshlrev_b32_e32 v208, 16, v192
	v_and_b32_e32 v209, 0xffff0000, v192
	v_lshlrev_b32_e32 v216, 16, v200
	v_and_b32_e32 v217, 0xffff0000, v200
	v_pk_fma_f32 v[86:87], v[86:87], v[208:209], v[216:217]
	v_lshlrev_b32_e32 v210, 16, v193
	v_and_b32_e32 v211, 0xffff0000, v193
	v_lshlrev_b32_e32 v218, 16, v201
	v_and_b32_e32 v219, 0xffff0000, v201
	v_pk_fma_f32 v[88:89], v[88:89], v[210:211], v[218:219]
	v_lshlrev_b32_e32 v212, 16, v194
	v_and_b32_e32 v213, 0xffff0000, v194
	v_lshlrev_b32_e32 v220, 16, v202
	v_and_b32_e32 v221, 0xffff0000, v202
	v_pk_fma_f32 v[82:83], v[82:83], v[212:213], v[220:221]
	v_lshlrev_b32_e32 v214, 16, v195
	v_and_b32_e32 v215, 0xffff0000, v195
	v_lshlrev_b32_e32 v222, 16, v203
	v_and_b32_e32 v223, 0xffff0000, v203
	v_pk_fma_f32 v[84:85], v[84:85], v[214:215], v[222:223]
	v_cvt_pk_bf16_f32 v224, v86, v87
	v_cvt_pk_bf16_f32 v225, v88, v89
	v_cvt_pk_bf16_f32 v226, v82, v83
	v_cvt_pk_bf16_f32 v227, v84, v85
	v_lshlrev_b32_e32 v208, 16, v196
	v_and_b32_e32 v209, 0xffff0000, v196
	v_lshlrev_b32_e32 v216, 16, v204
	v_and_b32_e32 v217, 0xffff0000, v204
	v_pk_fma_f32 v[70:71], v[70:71], v[208:209], v[216:217]
	v_lshlrev_b32_e32 v210, 16, v197
	v_and_b32_e32 v211, 0xffff0000, v197
	v_lshlrev_b32_e32 v218, 16, v205
	v_and_b32_e32 v219, 0xffff0000, v205
	v_pk_fma_f32 v[72:73], v[72:73], v[210:211], v[218:219]
	v_lshlrev_b32_e32 v212, 16, v198
	v_and_b32_e32 v213, 0xffff0000, v198
	v_lshlrev_b32_e32 v220, 16, v206
	v_and_b32_e32 v221, 0xffff0000, v206
	v_pk_fma_f32 v[66:67], v[66:67], v[212:213], v[220:221]
	v_lshlrev_b32_e32 v214, 16, v199
	v_and_b32_e32 v215, 0xffff0000, v199
	v_lshlrev_b32_e32 v222, 16, v207
	v_and_b32_e32 v223, 0xffff0000, v207
	v_pk_fma_f32 v[68:69], v[68:69], v[214:215], v[222:223]
	v_cvt_pk_bf16_f32 v228, v70, v71
	v_cvt_pk_bf16_f32 v229, v72, v73
	v_cvt_pk_bf16_f32 v230, v66, v67
	v_cvt_pk_bf16_f32 v231, v68, v69
	global_store_dwordx4 v[236:237], v[224:227], off
	global_store_dwordx4 v[236:237], v[228:231], off offset:256
	v_lshl_add_u64 v[236:237], v[236:237], 0, s[4:5]
	v_permlane16_swap_b32_e32 v62, v58
	v_permlane16_swap_b32_e32 v63, v59
	v_permlane16_swap_b32_e32 v64, v60
	v_permlane16_swap_b32_e32 v65, v61
	v_permlane16_swap_b32_e32 v54, v50
	v_permlane16_swap_b32_e32 v55, v51
	v_permlane16_swap_b32_e32 v56, v52
	v_permlane16_swap_b32_e32 v57, v53
	s_mov_b64 s[4:5], 0x8000
	v_lshl_add_u64 v[232:233], v[232:233], 0, s[4:5]
	v_lshl_add_u64 v[234:235], v[234:235], 0, s[4:5]
	global_load_dwordx4 v[192:195], v[232:233], off
	global_load_dwordx4 v[196:199], v[232:233], off offset:256
	global_load_dwordx4 v[200:203], v[234:235], off
	global_load_dwordx4 v[204:207], v[234:235], off offset:256
	s_waitcnt vmcnt(6)
	v_lshlrev_b32_e32 v208, 16, v176
	v_and_b32_e32 v209, 0xffff0000, v176
	v_lshlrev_b32_e32 v216, 16, v184
	v_and_b32_e32 v217, 0xffff0000, v184
	v_pk_fma_f32 v[62:63], v[62:63], v[208:209], v[216:217]
	v_lshlrev_b32_e32 v210, 16, v177
	v_and_b32_e32 v211, 0xffff0000, v177
	v_lshlrev_b32_e32 v218, 16, v185
	v_and_b32_e32 v219, 0xffff0000, v185
	v_pk_fma_f32 v[64:65], v[64:65], v[210:211], v[218:219]
	v_lshlrev_b32_e32 v212, 16, v178
	v_and_b32_e32 v213, 0xffff0000, v178
	v_lshlrev_b32_e32 v220, 16, v186
	v_and_b32_e32 v221, 0xffff0000, v186
	v_pk_fma_f32 v[58:59], v[58:59], v[212:213], v[220:221]
	v_lshlrev_b32_e32 v214, 16, v179
	v_and_b32_e32 v215, 0xffff0000, v179
	v_lshlrev_b32_e32 v222, 16, v187
	v_and_b32_e32 v223, 0xffff0000, v187
	v_pk_fma_f32 v[60:61], v[60:61], v[214:215], v[222:223]
	v_cvt_pk_bf16_f32 v224, v62, v63
	v_cvt_pk_bf16_f32 v225, v64, v65
	v_cvt_pk_bf16_f32 v226, v58, v59
	v_cvt_pk_bf16_f32 v227, v60, v61
	v_lshlrev_b32_e32 v208, 16, v180
	v_and_b32_e32 v209, 0xffff0000, v180
	v_lshlrev_b32_e32 v216, 16, v188
	v_and_b32_e32 v217, 0xffff0000, v188
	v_pk_fma_f32 v[54:55], v[54:55], v[208:209], v[216:217]
	v_lshlrev_b32_e32 v210, 16, v181
	v_and_b32_e32 v211, 0xffff0000, v181
	v_lshlrev_b32_e32 v218, 16, v189
	v_and_b32_e32 v219, 0xffff0000, v189
	v_pk_fma_f32 v[56:57], v[56:57], v[210:211], v[218:219]
	v_lshlrev_b32_e32 v212, 16, v182
	v_and_b32_e32 v213, 0xffff0000, v182
	v_lshlrev_b32_e32 v220, 16, v190
	v_and_b32_e32 v221, 0xffff0000, v190
	v_pk_fma_f32 v[50:51], v[50:51], v[212:213], v[220:221]
	v_lshlrev_b32_e32 v214, 16, v183
	v_and_b32_e32 v215, 0xffff0000, v183
	v_lshlrev_b32_e32 v222, 16, v191
	v_and_b32_e32 v223, 0xffff0000, v191
	v_pk_fma_f32 v[52:53], v[52:53], v[214:215], v[222:223]
	v_cvt_pk_bf16_f32 v228, v54, v55
	v_cvt_pk_bf16_f32 v229, v56, v57
	v_cvt_pk_bf16_f32 v230, v50, v51
	v_cvt_pk_bf16_f32 v231, v52, v53
	global_store_dwordx4 v[236:237], v[224:227], off
	global_store_dwordx4 v[236:237], v[228:231], off offset:256
	v_lshl_add_u64 v[236:237], v[236:237], 0, s[4:5]
	v_permlane16_swap_b32_e32 v46, v42
	v_permlane16_swap_b32_e32 v47, v43
	v_permlane16_swap_b32_e32 v48, v44
	v_permlane16_swap_b32_e32 v49, v45
	v_permlane16_swap_b32_e32 v38, v34
	v_permlane16_swap_b32_e32 v39, v35
	v_permlane16_swap_b32_e32 v40, v36
	v_permlane16_swap_b32_e32 v41, v37
	s_mov_b64 s[4:5], 0x8000
	v_lshl_add_u64 v[232:233], v[232:233], 0, s[4:5]
	v_lshl_add_u64 v[234:235], v[234:235], 0, s[4:5]
	global_load_dwordx4 v[176:179], v[232:233], off
	global_load_dwordx4 v[180:183], v[232:233], off offset:256
	global_load_dwordx4 v[184:187], v[234:235], off
	global_load_dwordx4 v[188:191], v[234:235], off offset:256
	s_waitcnt vmcnt(6)
; __device__ __forceinline__ float bflo(uint32_t v) { return __uint_as_float(v << 16); }
; __device__ __forceinline__ float bfhi(uint32_t v) { return __uint_as_float(v & 0xFFFF0000u); }
;   __device__ __forceinline__ void operator()(const acc8_t& acc, const pg8::Unit& u, int wr, int wc, int fr, int fq) const {
;     ...
;       for (int m = 0; m < 4; m++) {
;         const size_t token = EPI_TOKEN(u, ai, m);
; #pragma unroll
;         for (int bj = 0; bj < 2; bj++)
; #pragma unroll
;           for (int n = 0; n < 2; n++) {
;             const int f = EPI_COL(u, bj, n);
;             const uint2 gb = *(const uint2*)(GB + token * 1024 + f);
;             const uint2 mo = *(const uint2*)(M + token * 1024 + f);
;             uint2 o;
;             o.x = pack2(bflo(mo.x) + bflo(gb.x) * acc[ai][bj][m][n][0], bfhi(mo.x) + bfhi(gb.x) * acc[ai][bj][m][n][1]);
;             o.y = pack2(bflo(mo.y) + bflo(gb.y) * acc[ai][bj][m][n][2], bfhi(mo.y) + bfhi(gb.y) * acc[ai][bj][m][n][3]);
;             *(uint2*)(M + token * 1024 + f) = o;
	v_lshlrev_b32_e32 v208, 16, v192
	v_and_b32_e32 v209, 0xffff0000, v192
	v_lshlrev_b32_e32 v216, 16, v200
	v_and_b32_e32 v217, 0xffff0000, v200
	v_pk_fma_f32 v[46:47], v[46:47], v[208:209], v[216:217]
	v_lshlrev_b32_e32 v210, 16, v193
	v_and_b32_e32 v211, 0xffff0000, v193
	v_lshlrev_b32_e32 v218, 16, v201
	v_and_b32_e32 v219, 0xffff0000, v201
	v_pk_fma_f32 v[48:49], v[48:49], v[210:211], v[218:219]
	v_lshlrev_b32_e32 v212, 16, v194
	v_and_b32_e32 v213, 0xffff0000, v194
	v_lshlrev_b32_e32 v220, 16, v202
	v_and_b32_e32 v221, 0xffff0000, v202
	v_pk_fma_f32 v[42:43], v[42:43], v[212:213], v[220:221]
	v_lshlrev_b32_e32 v214, 16, v195
	v_and_b32_e32 v215, 0xffff0000, v195
	v_lshlrev_b32_e32 v222, 16, v203
	v_and_b32_e32 v223, 0xffff0000, v203
	v_pk_fma_f32 v[44:45], v[44:45], v[214:215], v[222:223]
	v_cvt_pk_bf16_f32 v224, v46, v47
	v_cvt_pk_bf16_f32 v225, v48, v49
	v_cvt_pk_bf16_f32 v226, v42, v43
	v_cvt_pk_bf16_f32 v227, v44, v45
	v_lshlrev_b32_e32 v208, 16, v196
	v_and_b32_e32 v209, 0xffff0000, v196
	v_lshlrev_b32_e32 v216, 16, v204
	v_and_b32_e32 v217, 0xffff0000, v204
	v_pk_fma_f32 v[38:39], v[38:39], v[208:209], v[216:217]
	v_lshlrev_b32_e32 v210, 16, v197
	v_and_b32_e32 v211, 0xffff0000, v197
	v_lshlrev_b32_e32 v218, 16, v205
	v_and_b32_e32 v219, 0xffff0000, v205
	v_pk_fma_f32 v[40:41], v[40:41], v[210:211], v[218:219]
	v_lshlrev_b32_e32 v212, 16, v198
	v_and_b32_e32 v213, 0xffff0000, v198
	v_lshlrev_b32_e32 v220, 16, v206
	v_and_b32_e32 v221, 0xffff0000, v206
	v_pk_fma_f32 v[34:35], v[34:35], v[212:213], v[220:221]
	v_lshlrev_b32_e32 v214, 16, v199
	v_and_b32_e32 v215, 0xffff0000, v199
	v_lshlrev_b32_e32 v222, 16, v207
	v_and_b32_e32 v223, 0xffff0000, v207
	v_pk_fma_f32 v[36:37], v[36:37], v[214:215], v[222:223]
	v_cvt_pk_bf16_f32 v228, v38, v39
	v_cvt_pk_bf16_f32 v229, v40, v41
	v_cvt_pk_bf16_f32 v230, v34, v35
	v_cvt_pk_bf16_f32 v231, v36, v37
	global_store_dwordx4 v[236:237], v[224:227], off
	global_store_dwordx4 v[236:237], v[228:231], off offset:256
	v_lshl_add_u64 v[236:237], v[236:237], 0, s[4:5]
	v_permlane16_swap_b32_e32 v30, v26
	v_permlane16_swap_b32_e32 v31, v27
	v_permlane16_swap_b32_e32 v32, v28
	v_permlane16_swap_b32_e32 v33, v29
	v_permlane16_swap_b32_e32 v22, v18
	v_permlane16_swap_b32_e32 v23, v19
	v_permlane16_swap_b32_e32 v24, v20
	v_permlane16_swap_b32_e32 v25, v21
	s_mov_b64 s[4:5], 0x8000
	v_lshl_add_u64 v[232:233], v[232:233], 0, s[4:5]
	v_lshl_add_u64 v[234:235], v[234:235], 0, s[4:5]
	global_load_dwordx4 v[192:195], v[232:233], off
	global_load_dwordx4 v[196:199], v[232:233], off offset:256
	global_load_dwordx4 v[200:203], v[234:235], off
	global_load_dwordx4 v[204:207], v[234:235], off offset:256
	s_waitcnt vmcnt(6)
; __device__ __forceinline__ float bflo(uint32_t v) { return __uint_as_float(v << 16); }
; __device__ __forceinline__ float bfhi(uint32_t v) { return __uint_as_float(v & 0xFFFF0000u); }
; #define PG8_WAIT_V(n) asm volatile("s_waitcnt vmcnt(" #n ")" ::: "memory")
; #define PG8_BAR __builtin_amdgcn_s_barrier()
; template <class Epi, class Sched>
; __device__ __forceinline__ void gemm_phase(PG8_LAS unsigned char* lds, const Gemm g, const Sched& S, const Epi& E) {
;     ...
;     PG8_WAIT_V(0);
;     if (wr == 0) PG8_BAR;
;     PG8_BAR;
;   __device__ __forceinline__ void operator()(const acc8_t& acc, const pg8::Unit& u, int wr, int wc, int fr, int fq) const {
;     ...
;       for (int m = 0; m < 4; m++) {
;         const size_t token = EPI_TOKEN(u, ai, m);
; #pragma unroll
;         for (int bj = 0; bj < 2; bj++)
; #pragma unroll
;           for (int n = 0; n < 2; n++) {
;             const int f = EPI_COL(u, bj, n);
;             const uint2 gb = *(const uint2*)(GB + token * 1024 + f);
;             const uint2 mo = *(const uint2*)(M + token * 1024 + f);
;             uint2 o;
;             o.x = pack2(bflo(mo.x) + bflo(gb.x) * acc[ai][bj][m][n][0], bfhi(mo.x) + bfhi(gb.x) * acc[ai][bj][m][n][1]);
;             o.y = pack2(bflo(mo.y) + bflo(gb.y) * acc[ai][bj][m][n][2], bfhi(mo.y) + bfhi(gb.y) * acc[ai][bj][m][n][3]);
;             *(uint2*)(M + token * 1024 + f) = o;
	v_lshlrev_b32_e32 v208, 16, v176
	v_and_b32_e32 v209, 0xffff0000, v176
	v_lshlrev_b32_e32 v216, 16, v184
	v_and_b32_e32 v217, 0xffff0000, v184
	v_pk_fma_f32 v[30:31], v[30:31], v[208:209], v[216:217]
	v_lshlrev_b32_e32 v210, 16, v177
	v_and_b32_e32 v211, 0xffff0000, v177
	v_lshlrev_b32_e32 v218, 16, v185
	v_and_b32_e32 v219, 0xffff0000, v185
	v_pk_fma_f32 v[32:33], v[32:33], v[210:211], v[218:219]
	v_lshlrev_b32_e32 v212, 16, v178
	v_and_b32_e32 v213, 0xffff0000, v178
	v_lshlrev_b32_e32 v220, 16, v186
	v_and_b32_e32 v221, 0xffff0000, v186
	v_pk_fma_f32 v[26:27], v[26:27], v[212:213], v[220:221]
	v_lshlrev_b32_e32 v214, 16, v179
	v_and_b32_e32 v215, 0xffff0000, v179
	v_lshlrev_b32_e32 v222, 16, v187
	v_and_b32_e32 v223, 0xffff0000, v187
	v_pk_fma_f32 v[28:29], v[28:29], v[214:215], v[222:223]
	v_cvt_pk_bf16_f32 v224, v30, v31
	v_cvt_pk_bf16_f32 v225, v32, v33
	v_cvt_pk_bf16_f32 v226, v26, v27
	v_cvt_pk_bf16_f32 v227, v28, v29
	v_lshlrev_b32_e32 v208, 16, v180
	v_and_b32_e32 v209, 0xffff0000, v180
	v_lshlrev_b32_e32 v216, 16, v188
	v_and_b32_e32 v217, 0xffff0000, v188
	v_pk_fma_f32 v[22:23], v[22:23], v[208:209], v[216:217]
	v_lshlrev_b32_e32 v210, 16, v181
	v_and_b32_e32 v211, 0xffff0000, v181
	v_lshlrev_b32_e32 v218, 16, v189
	v_and_b32_e32 v219, 0xffff0000, v189
	v_pk_fma_f32 v[24:25], v[24:25], v[210:211], v[218:219]
	v_lshlrev_b32_e32 v212, 16, v182
	v_and_b32_e32 v213, 0xffff0000, v182
	v_lshlrev_b32_e32 v220, 16, v190
	v_and_b32_e32 v221, 0xffff0000, v190
	v_pk_fma_f32 v[18:19], v[18:19], v[212:213], v[220:221]
	v_lshlrev_b32_e32 v214, 16, v183
	v_and_b32_e32 v215, 0xffff0000, v183
	v_lshlrev_b32_e32 v222, 16, v191
	v_and_b32_e32 v223, 0xffff0000, v191
	v_pk_fma_f32 v[20:21], v[20:21], v[214:215], v[222:223]
	v_cvt_pk_bf16_f32 v228, v22, v23
	v_cvt_pk_bf16_f32 v229, v24, v25
	v_cvt_pk_bf16_f32 v230, v18, v19
	v_cvt_pk_bf16_f32 v231, v20, v21
	global_store_dwordx4 v[236:237], v[224:227], off
	global_store_dwordx4 v[236:237], v[228:231], off offset:256
	v_lshl_add_u64 v[236:237], v[236:237], 0, s[4:5]
	v_permlane16_swap_b32_e32 v14, v10
	v_permlane16_swap_b32_e32 v15, v11
	v_permlane16_swap_b32_e32 v16, v12
	v_permlane16_swap_b32_e32 v17, v13
	v_permlane16_swap_b32_e32 v6, v2
	v_permlane16_swap_b32_e32 v7, v3
	v_permlane16_swap_b32_e32 v8, v4
	v_permlane16_swap_b32_e32 v9, v5
	s_waitcnt vmcnt(2)
	v_lshlrev_b32_e32 v208, 16, v192
	v_and_b32_e32 v209, 0xffff0000, v192
	v_lshlrev_b32_e32 v216, 16, v200
	v_and_b32_e32 v217, 0xffff0000, v200
	v_pk_fma_f32 v[14:15], v[14:15], v[208:209], v[216:217]
	v_lshlrev_b32_e32 v210, 16, v193
	v_and_b32_e32 v211, 0xffff0000, v193
	v_lshlrev_b32_e32 v218, 16, v201
	v_and_b32_e32 v219, 0xffff0000, v201
	v_pk_fma_f32 v[16:17], v[16:17], v[210:211], v[218:219]
	v_lshlrev_b32_e32 v212, 16, v194
	v_and_b32_e32 v213, 0xffff0000, v194
	v_lshlrev_b32_e32 v220, 16, v202
	v_and_b32_e32 v221, 0xffff0000, v202
	v_pk_fma_f32 v[10:11], v[10:11], v[212:213], v[220:221]
	v_lshlrev_b32_e32 v214, 16, v195
	v_and_b32_e32 v215, 0xffff0000, v195
	v_lshlrev_b32_e32 v222, 16, v203
	v_and_b32_e32 v223, 0xffff0000, v203
	v_pk_fma_f32 v[12:13], v[12:13], v[214:215], v[222:223]
	v_cvt_pk_bf16_f32 v224, v14, v15
	v_cvt_pk_bf16_f32 v225, v16, v17
	v_cvt_pk_bf16_f32 v226, v10, v11
	v_cvt_pk_bf16_f32 v227, v12, v13
	v_lshlrev_b32_e32 v208, 16, v196
	v_and_b32_e32 v209, 0xffff0000, v196
	v_lshlrev_b32_e32 v216, 16, v204
	v_and_b32_e32 v217, 0xffff0000, v204
	v_pk_fma_f32 v[6:7], v[6:7], v[208:209], v[216:217]
	v_lshlrev_b32_e32 v210, 16, v197
	v_and_b32_e32 v211, 0xffff0000, v197
	v_lshlrev_b32_e32 v218, 16, v205
	v_and_b32_e32 v219, 0xffff0000, v205
	v_pk_fma_f32 v[8:9], v[8:9], v[210:211], v[218:219]
	v_lshlrev_b32_e32 v212, 16, v198
	v_and_b32_e32 v213, 0xffff0000, v198
	v_lshlrev_b32_e32 v220, 16, v206
	v_and_b32_e32 v221, 0xffff0000, v206
	v_pk_fma_f32 v[2:3], v[2:3], v[212:213], v[220:221]
	v_lshlrev_b32_e32 v214, 16, v199
	v_and_b32_e32 v215, 0xffff0000, v199
	v_lshlrev_b32_e32 v222, 16, v207
	v_and_b32_e32 v223, 0xffff0000, v207
	v_pk_fma_f32 v[4:5], v[4:5], v[214:215], v[222:223]
	v_cvt_pk_bf16_f32 v228, v6, v7
	v_cvt_pk_bf16_f32 v229, v8, v9
	v_cvt_pk_bf16_f32 v230, v2, v3
	v_cvt_pk_bf16_f32 v231, v4, v5
	global_store_dwordx4 v[236:237], v[224:227], off
	global_store_dwordx4 v[236:237], v[228:231], off offset:256
	s_and_b64 vcc, exec, s[16:17]
	s_cbranch_vccz .LBB0_707
	s_waitcnt vmcnt(0)
	s_cmpk_gt_u32 s33, 0xff
	s_cbranch_scc1 .LBB0_717
	s_barrier
